# EpiResid (out-proj, FFN2 down): XB residual loads prefetched at K-loop exit, counted vmcnt, on top of SwiGLU hoist
# speedup vs baseline: 1.0079x; 1.0079x over previous
; #define PG8_STAGE(bufoff, gbase, voff) do { _Pragma("unroll") for (int _i = 0; _i < 2; ++_i) \
;         __builtin_amdgcn_global_load_lds((const unsigned*)((const char*)(gbase) + (voff)[_i]), (PG8_LAS unsigned*)(lds + (bufoff) + ldsw + _i * 8192), 16, 0, 0); } while (0)
; #define PG8_LDA(dst, b, h) do { _Pragma("unroll") for (int m = 0; m < 4; ++m) _Pragma("unroll") for (int k = 0; k < 2; ++k) dst[m][k] = *(const PG8_LAS bf16x8*)(lds + PG8_SA(b, h) + aoff + m * 2048 + k * 1024); } while (0)
; #define PG8_LDB(dst, b, h) do { _Pragma("unroll") for (int n = 0; n < 2; ++n) _Pragma("unroll") for (int k = 0; k < 2; ++k) dst[n][k] = *(const PG8_LAS bf16x8*)(lds + PG8_SB(b, h) + boff + n * 2048 + k * 1024); } while (0)
; #define PG8_MMA_NP(ai, bj, At, Bt) do { _Pragma("unroll") for (int m = 0; m < 4; ++m) _Pragma("unroll") for (int n = 0; n < 2; ++n) _Pragma("unroll") for (int k = 0; k < 2; ++k) \
;         acc[ai][bj][m][n] = __builtin_amdgcn_mfma_f32_16x16x32_bf16(Bt[n][k], At[m][k], acc[ai][bj][m][n], 0, 0, 0); } while (0)
; #define PG8_BAR __builtin_amdgcn_s_barrier()
; template <class Epi, class Sched, bool ALIGN_EPI = false, bool SP2 = false>
; __device__ __forceinline__ void gemm_phase(PG8_LAS unsigned char* lds, const Gemm g, const Sched& S, const Epi& E) {
;     ...
;         for (int t = 0; t < nt; t += 2) {
;             const bool last = (t == nt - 2);
;             const char* a1 = cA + (size_t)(t + 1) * kstep;
;             const char* a2 = last ? nA : cA + (size_t)(t + 2) * kstep; const char* b2 = last ? nB : cB + (size_t)(t + 2) * kstep;
;             const char* a3 = a2 + kstep; const char* b3 = b2 + kstep;
;             if (last && has_next) S.a_ready(nxt);
;             if constexpr (SP2) {
;             PG8_LDB(B0, 0, 0); PG8_LDB(B1, 0, 1); PG8_SCHED; PG8_LDA(At, 0, 0); PG8_STAGE(PG8_SA(1, 1), a1 + hstep, voffA);
;             PG8_WAIT_V(8); PG8_WAIT_L(0); PG8_BAR; __builtin_amdgcn_s_setprio(1); PG8_MMA_NP(0, 0, At, B0); PG8_MMA_NP(0, 1, At, B1); __builtin_amdgcn_s_setprio(0); PG8_BAR; PG8_SCHED;
;             PG8_LDA(At, 0, 1); PG8_STAGE(PG8_SB(0, 0), b2, voffB); PG8_STAGE(PG8_SB(0, 1), b2 + hstep, voffB); PG8_STAGE(PG8_SA(0, 0), a2, voffA);
;             PG8_WAIT_V(8); PG8_WAIT_L(0); PG8_BAR; __builtin_amdgcn_s_setprio(1); PG8_MMA_NP(1, 0, At, B0); PG8_MMA_NP(1, 1, At, B1); __builtin_amdgcn_s_setprio(0); PG8_BAR; PG8_SCHED;
.LBB0_1016:
	s_add_u32 s14, s12, 0xfffc0080
	s_addc_u32 s15, s13, -1
	s_add_i32 s22, 0, 0x10000
	s_cmp_eq_u32 s66, 12
	s_cselect_b32 s39, s29, s15
	s_cselect_b32 s38, s30, s14
	v_add_u32_e32 v144, s22, v147
	s_cselect_b32 s15, s49, s65
	s_cselect_b32 s14, s51, s64
	s_add_i32 s67, 0, 0x14000
	ds_read_b128 v[140:143], v144
	ds_read_b128 v[150:153], v144 offset:1024
	ds_read_b128 v[154:157], v144 offset:2048
	ds_read_b128 v[158:161], v144 offset:3072
	v_add_u32_e32 v144, s67, v147
	ds_read_b128 v[178:181], v144
	ds_read_b128 v[182:185], v144 offset:1024
	ds_read_b128 v[186:189], v144 offset:2048
	ds_read_b128 v[202:205], v144 offset:3072
	v_lshl_add_u64 v[144:145], s[12:13], 0, v[136:137]
	s_add_i32 m0, s56, 0xc000
	ds_read_b128 v[206:209], v149
	ds_read_b128 v[210:213], v149 offset:1024
	ds_read_b128 v[214:217], v149 offset:2048
	ds_read_b128 v[218:221], v149 offset:3072
	ds_read_b128 v[222:225], v149 offset:4096
	ds_read_b128 v[226:229], v149 offset:5120
	ds_read_b128 v[230:233], v149 offset:6144
	ds_read_b128 v[234:237], v149 offset:7168
	global_load_lds_dwordx4 v[144:145], off
	v_lshl_add_u64 v[144:145], s[12:13], 0, v[138:139]
	s_add_i32 m0, s56, 0xe000
	s_nop 0
	global_load_lds_dwordx4 v[144:145], off
	s_waitcnt vmcnt(8)
	s_waitcnt lgkmcnt(0)
	s_barrier
	s_setprio 1
	s_waitcnt lgkmcnt(0)
	v_mfma_f32_16x16x32_bf16 v[126:129], v[140:143], v[206:209], v[126:129]
	v_mfma_f32_16x16x32_bf16 v[122:125], v[154:157], v[206:209], v[122:125]
	v_mfma_f32_16x16x32_bf16 v[110:113], v[140:143], v[214:217], v[110:113]
	v_mfma_f32_16x16x32_bf16 v[106:109], v[154:157], v[214:217], v[106:109]
	v_mfma_f32_16x16x32_bf16 v[94:97], v[140:143], v[222:225], v[94:97]
	v_mfma_f32_16x16x32_bf16 v[90:93], v[154:157], v[222:225], v[90:93]
	v_mfma_f32_16x16x32_bf16 v[78:81], v[140:143], v[230:233], v[78:81]
	v_mfma_f32_16x16x32_bf16 v[74:77], v[154:157], v[230:233], v[74:77]
	v_mfma_f32_16x16x32_bf16 v[118:121], v[178:181], v[206:209], v[118:121]
	v_mfma_f32_16x16x32_bf16 v[114:117], v[186:189], v[206:209], v[114:117]
	v_mfma_f32_16x16x32_bf16 v[102:105], v[178:181], v[214:217], v[102:105]
	v_mfma_f32_16x16x32_bf16 v[98:101], v[186:189], v[214:217], v[98:101]
	v_mfma_f32_16x16x32_bf16 v[86:89], v[178:181], v[222:225], v[86:89]
	v_mfma_f32_16x16x32_bf16 v[82:85], v[186:189], v[222:225], v[82:85]
	v_mfma_f32_16x16x32_bf16 v[70:73], v[178:181], v[230:233], v[70:73]
	v_mfma_f32_16x16x32_bf16 v[66:69], v[186:189], v[230:233], v[66:69]
	v_mfma_f32_16x16x32_bf16 v[126:129], v[150:153], v[210:213], v[126:129]
	v_mfma_f32_16x16x32_bf16 v[122:125], v[158:161], v[210:213], v[122:125]
	v_mfma_f32_16x16x32_bf16 v[110:113], v[150:153], v[218:221], v[110:113]
	v_mfma_f32_16x16x32_bf16 v[106:109], v[158:161], v[218:221], v[106:109]
	v_mfma_f32_16x16x32_bf16 v[94:97], v[150:153], v[226:229], v[94:97]
	v_mfma_f32_16x16x32_bf16 v[90:93], v[158:161], v[226:229], v[90:93]
	v_mfma_f32_16x16x32_bf16 v[78:81], v[150:153], v[234:237], v[78:81]
	v_mfma_f32_16x16x32_bf16 v[74:77], v[158:161], v[234:237], v[74:77]
	v_mfma_f32_16x16x32_bf16 v[118:121], v[182:185], v[210:213], v[118:121]
	v_mfma_f32_16x16x32_bf16 v[114:117], v[202:205], v[210:213], v[114:117]
	v_mfma_f32_16x16x32_bf16 v[102:105], v[182:185], v[218:221], v[102:105]
	v_mfma_f32_16x16x32_bf16 v[98:101], v[202:205], v[218:221], v[98:101]
	v_mfma_f32_16x16x32_bf16 v[86:89], v[182:185], v[226:229], v[86:89]
	v_mfma_f32_16x16x32_bf16 v[82:85], v[202:205], v[226:229], v[82:85]
	v_mfma_f32_16x16x32_bf16 v[70:73], v[182:185], v[234:237], v[70:73]
	v_mfma_f32_16x16x32_bf16 v[66:69], v[202:205], v[234:237], v[66:69]
	s_setprio 0
	s_barrier
	s_add_i32 s22, s22, s41
	v_lshl_add_u64 v[144:145], s[14:15], 0, v[0:1]
	s_mov_b32 m0, s22
	ds_read_b128 v[206:209], v149 offset:16384
	ds_read_b128 v[210:213], v149 offset:17408
	ds_read_b128 v[214:217], v149 offset:18432
	ds_read_b128 v[218:221], v149 offset:19456
	ds_read_b128 v[222:225], v149 offset:20480
	ds_read_b128 v[226:229], v149 offset:21504
	ds_read_b128 v[230:233], v149 offset:22528
	ds_read_b128 v[234:237], v149 offset:23552
	global_load_lds_dwordx4 v[144:145], off
	s_add_i32 m0, s22, 0x2000
	s_add_u32 s22, s14, 0x40000
	v_lshl_add_u64 v[162:163], s[14:15], 0, v[130:131]
	s_addc_u32 s23, s15, 0
	s_add_i32 s67, s67, s41
	global_load_lds_dwordx4 v[162:163], off
	v_lshl_add_u64 v[190:191], s[22:23], 0, v[0:1]
	s_mov_b32 m0, s67
	v_lshl_add_u64 v[238:239], s[38:39], 0, v[132:133]
	global_load_lds_dwordx4 v[190:191], off
	v_lshl_add_u64 v[190:191], s[22:23], 0, v[130:131]
	s_add_i32 m0, s67, 0x2000
	s_nop 0
	global_load_lds_dwordx4 v[190:191], off
	v_lshl_add_u64 v[190:191], s[38:39], 0, v[134:135]
	s_mov_b32 m0, s56
	s_nop 0
	global_load_lds_dwordx4 v[190:191], off
	s_mov_b32 m0, s57
	s_nop 0
	global_load_lds_dwordx4 v[238:239], off
	s_waitcnt vmcnt(8)
	s_waitcnt lgkmcnt(0)
	s_barrier
; #define PG8_STAGE(bufoff, gbase, voff) do { _Pragma("unroll") for (int _i = 0; _i < 2; ++_i) \
;         __builtin_amdgcn_global_load_lds((const unsigned*)((const char*)(gbase) + (voff)[_i]), (PG8_LAS unsigned*)(lds + (bufoff) + ldsw + _i * 8192), 16, 0, 0); } while (0)
; #define PG8_LDA(dst, b, h) do { _Pragma("unroll") for (int m = 0; m < 4; ++m) _Pragma("unroll") for (int k = 0; k < 2; ++k) dst[m][k] = *(const PG8_LAS bf16x8*)(lds + PG8_SA(b, h) + aoff + m * 2048 + k * 1024); } while (0)
; #define PG8_LDB(dst, b, h) do { _Pragma("unroll") for (int n = 0; n < 2; ++n) _Pragma("unroll") for (int k = 0; k < 2; ++k) dst[n][k] = *(const PG8_LAS bf16x8*)(lds + PG8_SB(b, h) + boff + n * 2048 + k * 1024); } while (0)
; #define PG8_MMA_NP(ai, bj, At, Bt) do { _Pragma("unroll") for (int m = 0; m < 4; ++m) _Pragma("unroll") for (int n = 0; n < 2; ++n) _Pragma("unroll") for (int k = 0; k < 2; ++k) \
;         acc[ai][bj][m][n] = __builtin_amdgcn_mfma_f32_16x16x32_bf16(Bt[n][k], At[m][k], acc[ai][bj][m][n], 0, 0, 0); } while (0)
; #define PG8_WAIT_V(n) asm volatile("s_waitcnt vmcnt(" #n ")" ::: "memory")
; #define PG8_WAIT_L(n) asm volatile("s_waitcnt lgkmcnt(" #n ")" ::: "memory")
; #define PG8_BAR __builtin_amdgcn_s_barrier()
; #define PG8_SCHED __builtin_amdgcn_sched_barrier(0)
; template <class Epi, class Sched, bool ALIGN_EPI = false, bool SP2 = false>
; __device__ __forceinline__ void gemm_phase(PG8_LAS unsigned char* lds, const Gemm g, const Sched& S, const Epi& E) {
;     ...
;             PG8_WAIT_V(8); PG8_WAIT_L(0); PG8_BAR; __builtin_amdgcn_s_setprio(1); PG8_MMA_NP(1, 0, At, B0); PG8_MMA_NP(1, 1, At, B1); __builtin_amdgcn_s_setprio(0); PG8_BAR; PG8_SCHED;
;             PG8_LDB(B0, 1, 0); PG8_LDB(B1, 1, 1); PG8_SCHED; PG8_LDA(At, 1, 0); PG8_STAGE(PG8_SA(0, 1), a2 + hstep, voffA);
;             PG8_WAIT_V(8); PG8_WAIT_L(0); PG8_BAR; __builtin_amdgcn_s_setprio(1); PG8_MMA_NP(0, 0, At, B0); PG8_MMA_NP(0, 1, At, B1); __builtin_amdgcn_s_setprio(0); PG8_BAR; PG8_SCHED;
	s_setprio 1
	s_waitcnt lgkmcnt(0)
	v_mfma_f32_16x16x32_bf16 v[62:65], v[140:143], v[206:209], v[62:65]
	v_mfma_f32_16x16x32_bf16 v[58:61], v[154:157], v[206:209], v[58:61]
	v_mfma_f32_16x16x32_bf16 v[46:49], v[140:143], v[214:217], v[46:49]
	v_mfma_f32_16x16x32_bf16 v[42:45], v[154:157], v[214:217], v[42:45]
	v_mfma_f32_16x16x32_bf16 v[30:33], v[140:143], v[222:225], v[30:33]
	v_mfma_f32_16x16x32_bf16 v[26:29], v[154:157], v[222:225], v[26:29]
	v_mfma_f32_16x16x32_bf16 v[14:17], v[140:143], v[230:233], v[14:17]
	v_mfma_f32_16x16x32_bf16 v[10:13], v[154:157], v[230:233], v[10:13]
	v_mfma_f32_16x16x32_bf16 v[54:57], v[178:181], v[206:209], v[54:57]
	v_mfma_f32_16x16x32_bf16 v[50:53], v[186:189], v[206:209], v[50:53]
	v_mfma_f32_16x16x32_bf16 v[38:41], v[178:181], v[214:217], v[38:41]
	v_mfma_f32_16x16x32_bf16 v[34:37], v[186:189], v[214:217], v[34:37]
	v_mfma_f32_16x16x32_bf16 v[22:25], v[178:181], v[222:225], v[22:25]
	v_mfma_f32_16x16x32_bf16 v[18:21], v[186:189], v[222:225], v[18:21]
	v_mfma_f32_16x16x32_bf16 v[6:9], v[178:181], v[230:233], v[6:9]
	v_mfma_f32_16x16x32_bf16 v[2:5], v[186:189], v[230:233], v[2:5]
	v_mfma_f32_16x16x32_bf16 v[62:65], v[150:153], v[210:213], v[62:65]
	v_mfma_f32_16x16x32_bf16 v[58:61], v[158:161], v[210:213], v[58:61]
	v_mfma_f32_16x16x32_bf16 v[46:49], v[150:153], v[218:221], v[46:49]
	v_mfma_f32_16x16x32_bf16 v[42:45], v[158:161], v[218:221], v[42:45]
	v_mfma_f32_16x16x32_bf16 v[30:33], v[150:153], v[226:229], v[30:33]
	v_mfma_f32_16x16x32_bf16 v[26:29], v[158:161], v[226:229], v[26:29]
	v_mfma_f32_16x16x32_bf16 v[14:17], v[150:153], v[234:237], v[14:17]
	v_mfma_f32_16x16x32_bf16 v[10:13], v[158:161], v[234:237], v[10:13]
	v_mfma_f32_16x16x32_bf16 v[54:57], v[182:185], v[210:213], v[54:57]
	v_mfma_f32_16x16x32_bf16 v[50:53], v[202:205], v[210:213], v[50:53]
	v_mfma_f32_16x16x32_bf16 v[38:41], v[182:185], v[218:221], v[38:41]
	v_mfma_f32_16x16x32_bf16 v[34:37], v[202:205], v[218:221], v[34:37]
	v_mfma_f32_16x16x32_bf16 v[22:25], v[182:185], v[226:229], v[22:25]
	v_mfma_f32_16x16x32_bf16 v[18:21], v[202:205], v[226:229], v[18:21]
	v_mfma_f32_16x16x32_bf16 v[6:9], v[182:185], v[234:237], v[6:9]
	v_mfma_f32_16x16x32_bf16 v[2:5], v[202:205], v[234:237], v[2:5]
	s_setprio 0
	s_barrier
	s_add_i32 s67, 0, 0x18000
	s_add_i32 s68, 0, 0x1c000
	v_add_u32_e32 v158, s67, v147
	v_add_u32_e32 v202, s68, v147
	ds_read_b128 v[140:143], v158
	ds_read_b128 v[150:153], v158 offset:1024
	ds_read_b128 v[154:157], v158 offset:2048
	ds_read_b128 v[158:161], v158 offset:3072
	ds_read_b128 v[178:181], v202
	ds_read_b128 v[182:185], v202 offset:1024
	ds_read_b128 v[186:189], v202 offset:2048
	ds_read_b128 v[202:205], v202 offset:3072
	s_add_u32 s22, s38, 0x40000
	s_addc_u32 s23, s39, 0
	s_mov_b32 m0, s58
	v_lshl_add_u64 v[240:241], s[22:23], 0, v[134:135]
	ds_read_b128 v[206:209], v149 offset:32768
	ds_read_b128 v[210:213], v149 offset:33792
	ds_read_b128 v[214:217], v149 offset:34816
	ds_read_b128 v[218:221], v149 offset:35840
	ds_read_b128 v[222:225], v149 offset:36864
	ds_read_b128 v[226:229], v149 offset:37888
	ds_read_b128 v[230:233], v149 offset:38912
	ds_read_b128 v[234:237], v149 offset:39936
	global_load_lds_dwordx4 v[240:241], off
	v_lshl_add_u64 v[240:241], s[22:23], 0, v[132:133]
	s_mov_b32 m0, s59
	s_nop 0
	global_load_lds_dwordx4 v[240:241], off
	s_waitcnt vmcnt(8)
	s_waitcnt lgkmcnt(0)
	s_barrier
	s_setprio 1
	s_waitcnt lgkmcnt(0)
	v_mfma_f32_16x16x32_bf16 v[126:129], v[140:143], v[206:209], v[126:129]
	v_mfma_f32_16x16x32_bf16 v[122:125], v[154:157], v[206:209], v[122:125]
	v_mfma_f32_16x16x32_bf16 v[110:113], v[140:143], v[214:217], v[110:113]
	v_mfma_f32_16x16x32_bf16 v[106:109], v[154:157], v[214:217], v[106:109]
	v_mfma_f32_16x16x32_bf16 v[94:97], v[140:143], v[222:225], v[94:97]
	v_mfma_f32_16x16x32_bf16 v[90:93], v[154:157], v[222:225], v[90:93]
	v_mfma_f32_16x16x32_bf16 v[78:81], v[140:143], v[230:233], v[78:81]
	v_mfma_f32_16x16x32_bf16 v[74:77], v[154:157], v[230:233], v[74:77]
	v_mfma_f32_16x16x32_bf16 v[118:121], v[178:181], v[206:209], v[118:121]
	v_mfma_f32_16x16x32_bf16 v[114:117], v[186:189], v[206:209], v[114:117]
	v_mfma_f32_16x16x32_bf16 v[102:105], v[178:181], v[214:217], v[102:105]
	v_mfma_f32_16x16x32_bf16 v[98:101], v[186:189], v[214:217], v[98:101]
	v_mfma_f32_16x16x32_bf16 v[86:89], v[178:181], v[222:225], v[86:89]
	v_mfma_f32_16x16x32_bf16 v[82:85], v[186:189], v[222:225], v[82:85]
	v_mfma_f32_16x16x32_bf16 v[70:73], v[178:181], v[230:233], v[70:73]
	v_mfma_f32_16x16x32_bf16 v[66:69], v[186:189], v[230:233], v[66:69]
	v_mfma_f32_16x16x32_bf16 v[126:129], v[150:153], v[210:213], v[126:129]
	v_mfma_f32_16x16x32_bf16 v[122:125], v[158:161], v[210:213], v[122:125]
	v_mfma_f32_16x16x32_bf16 v[110:113], v[150:153], v[218:221], v[110:113]
	v_mfma_f32_16x16x32_bf16 v[106:109], v[158:161], v[218:221], v[106:109]
	v_mfma_f32_16x16x32_bf16 v[94:97], v[150:153], v[226:229], v[94:97]
	v_mfma_f32_16x16x32_bf16 v[90:93], v[158:161], v[226:229], v[90:93]
	v_mfma_f32_16x16x32_bf16 v[78:81], v[150:153], v[234:237], v[78:81]
	v_mfma_f32_16x16x32_bf16 v[74:77], v[158:161], v[234:237], v[74:77]
	v_mfma_f32_16x16x32_bf16 v[118:121], v[182:185], v[210:213], v[118:121]
	v_mfma_f32_16x16x32_bf16 v[114:117], v[202:205], v[210:213], v[114:117]
	v_mfma_f32_16x16x32_bf16 v[102:105], v[182:185], v[218:221], v[102:105]
	v_mfma_f32_16x16x32_bf16 v[98:101], v[202:205], v[218:221], v[98:101]
	v_mfma_f32_16x16x32_bf16 v[86:89], v[182:185], v[226:229], v[86:89]
	v_mfma_f32_16x16x32_bf16 v[82:85], v[202:205], v[226:229], v[82:85]
	v_mfma_f32_16x16x32_bf16 v[70:73], v[182:185], v[234:237], v[70:73]
	v_mfma_f32_16x16x32_bf16 v[66:69], v[202:205], v[234:237], v[66:69]
	s_setprio 0
	s_barrier
; #define PG8_STAGE(bufoff, gbase, voff) do { _Pragma("unroll") for (int _i = 0; _i < 2; ++_i) \
;         __builtin_amdgcn_global_load_lds((const unsigned*)((const char*)(gbase) + (voff)[_i]), (PG8_LAS unsigned*)(lds + (bufoff) + ldsw + _i * 8192), 16, 0, 0); } while (0)
; #define PG8_LDA(dst, b, h) do { _Pragma("unroll") for (int m = 0; m < 4; ++m) _Pragma("unroll") for (int k = 0; k < 2; ++k) dst[m][k] = *(const PG8_LAS bf16x8*)(lds + PG8_SA(b, h) + aoff + m * 2048 + k * 1024); } while (0)
; #define PG8_MMA_NP(ai, bj, At, Bt) do { _Pragma("unroll") for (int m = 0; m < 4; ++m) _Pragma("unroll") for (int n = 0; n < 2; ++n) _Pragma("unroll") for (int k = 0; k < 2; ++k) \
;         acc[ai][bj][m][n] = __builtin_amdgcn_mfma_f32_16x16x32_bf16(Bt[n][k], At[m][k], acc[ai][bj][m][n], 0, 0, 0); } while (0)
; #define PG8_WAIT_V(n) asm volatile("s_waitcnt vmcnt(" #n ")" ::: "memory")
; #define PG8_WAIT_L(n) asm volatile("s_waitcnt lgkmcnt(" #n ")" ::: "memory")
; #define PG8_BAR __builtin_amdgcn_s_barrier()
; #define PG8_SCHED __builtin_amdgcn_sched_barrier(0)
; DI float bflo(unsigned w) { return __uint_as_float(w << 16); }
; template <class Epi, class Sched, bool ALIGN_EPI = false, bool SP2 = false>
; __device__ __forceinline__ void gemm_phase(PG8_LAS unsigned char* lds, const Gemm g, const Sched& S, const Epi& E) {
;     ...
;             PG8_LDA(At, 1, 1); PG8_STAGE(PG8_SB(1, 0), b3, voffB); PG8_STAGE(PG8_SB(1, 1), b3 + hstep, voffB); PG8_STAGE(PG8_SA(1, 0), a3, voffA);
;             PG8_WAIT_V(8); PG8_WAIT_L(0); PG8_BAR; __builtin_amdgcn_s_setprio(1); PG8_MMA_NP(1, 0, At, B0); PG8_MMA_NP(1, 1, At, B1); __builtin_amdgcn_s_setprio(0); PG8_BAR; PG8_SCHED;
;     DI void operator()(const f32x4 (&acc)[2][2][4][2], const pg8::Unit& u, int wr, int wc, int fr, int fq) const {
;     ...
;                 const int row = row0 + ai * 128 + m * 16; float ss = 0.f;
; #pragma unroll
;                 for (int bj = 0; bj < 2; ++bj) {
;                     const size_t off = (size_t)row * DM + col0 + bj * 128;
;                     f32x4 b0, b1;
;                     if (base32) { b0 = *(const f32x4*)(base32 + off); b1 = *(const f32x4*)(base32 + off + 4); }
;                     else { const u32x4 bb = *(const u32x4*)(XB + off); b0 = (f32x4){bflo(bb.x), bfhi(bb.x), bflo(bb.y), bfhi(bb.y)}; b1 = (f32x4){bflo(bb.z), bfhi(bb.z), bflo(bb.w), bfhi(bb.w)}; }
	s_add_i32 s22, s67, s41
	v_lshl_add_u64 v[144:145], v[144:145], 0, s[20:21]
	s_mov_b32 m0, s22
	ds_read_b128 v[206:209], v149 offset:49152
	ds_read_b128 v[210:213], v149 offset:50176
	ds_read_b128 v[214:217], v149 offset:51200
	ds_read_b128 v[218:221], v149 offset:52224
	ds_read_b128 v[222:225], v149 offset:53248
	ds_read_b128 v[226:229], v149 offset:54272
	ds_read_b128 v[230:233], v149 offset:55296
	ds_read_b128 v[234:237], v149 offset:56320
	global_load_lds_dwordx4 v[144:145], off
	s_add_i32 m0, s22, 0x2000
	s_add_u32 s14, s14, 0x40080
	v_lshl_add_u64 v[144:145], v[162:163], 0, s[20:21]
	s_addc_u32 s15, s15, 0
	s_add_i32 s22, s68, s41
	global_load_lds_dwordx4 v[144:145], off
	v_lshl_add_u64 v[144:145], s[14:15], 0, v[0:1]
	s_mov_b32 m0, s22
	s_nop 0
	global_load_lds_dwordx4 v[144:145], off
	v_lshl_add_u64 v[144:145], s[14:15], 0, v[130:131]
	s_add_i32 m0, s22, 0x2000
	s_nop 0
	global_load_lds_dwordx4 v[144:145], off
	v_lshl_add_u64 v[144:145], v[190:191], 0, s[20:21]
	s_mov_b32 m0, s61
	s_nop 0
	global_load_lds_dwordx4 v[144:145], off
	v_lshl_add_u64 v[144:145], v[238:239], 0, s[20:21]
	s_mov_b32 m0, s62
	s_nop 0
	global_load_lds_dwordx4 v[144:145], off
	s_waitcnt vmcnt(8)
	s_waitcnt lgkmcnt(0)
	s_barrier
	s_setprio 1
	s_waitcnt lgkmcnt(0)
	v_mfma_f32_16x16x32_bf16 v[62:65], v[140:143], v[206:209], v[62:65]
	v_mfma_f32_16x16x32_bf16 v[58:61], v[154:157], v[206:209], v[58:61]
	v_mfma_f32_16x16x32_bf16 v[46:49], v[140:143], v[214:217], v[46:49]
	v_mfma_f32_16x16x32_bf16 v[42:45], v[154:157], v[214:217], v[42:45]
	v_mfma_f32_16x16x32_bf16 v[30:33], v[140:143], v[222:225], v[30:33]
	v_mfma_f32_16x16x32_bf16 v[26:29], v[154:157], v[222:225], v[26:29]
	v_mfma_f32_16x16x32_bf16 v[14:17], v[140:143], v[230:233], v[14:17]
	v_mfma_f32_16x16x32_bf16 v[10:13], v[154:157], v[230:233], v[10:13]
	v_mfma_f32_16x16x32_bf16 v[54:57], v[178:181], v[206:209], v[54:57]
	v_mfma_f32_16x16x32_bf16 v[50:53], v[186:189], v[206:209], v[50:53]
	v_mfma_f32_16x16x32_bf16 v[38:41], v[178:181], v[214:217], v[38:41]
	v_mfma_f32_16x16x32_bf16 v[34:37], v[186:189], v[214:217], v[34:37]
	v_mfma_f32_16x16x32_bf16 v[22:25], v[178:181], v[222:225], v[22:25]
	v_mfma_f32_16x16x32_bf16 v[18:21], v[186:189], v[222:225], v[18:21]
	v_mfma_f32_16x16x32_bf16 v[6:9], v[178:181], v[230:233], v[6:9]
	v_mfma_f32_16x16x32_bf16 v[2:5], v[186:189], v[230:233], v[2:5]
	v_mfma_f32_16x16x32_bf16 v[62:65], v[150:153], v[210:213], v[62:65]
	v_mfma_f32_16x16x32_bf16 v[58:61], v[158:161], v[210:213], v[58:61]
	v_mfma_f32_16x16x32_bf16 v[46:49], v[150:153], v[218:221], v[46:49]
	v_mfma_f32_16x16x32_bf16 v[42:45], v[158:161], v[218:221], v[42:45]
	v_mfma_f32_16x16x32_bf16 v[30:33], v[150:153], v[226:229], v[30:33]
	v_mfma_f32_16x16x32_bf16 v[26:29], v[158:161], v[226:229], v[26:29]
	v_mfma_f32_16x16x32_bf16 v[14:17], v[150:153], v[234:237], v[14:17]
	v_mfma_f32_16x16x32_bf16 v[10:13], v[158:161], v[234:237], v[10:13]
	v_mfma_f32_16x16x32_bf16 v[54:57], v[182:185], v[210:213], v[54:57]
	v_mfma_f32_16x16x32_bf16 v[50:53], v[202:205], v[210:213], v[50:53]
	v_mfma_f32_16x16x32_bf16 v[38:41], v[182:185], v[218:221], v[38:41]
	v_mfma_f32_16x16x32_bf16 v[34:37], v[202:205], v[218:221], v[34:37]
	v_mfma_f32_16x16x32_bf16 v[22:25], v[182:185], v[226:229], v[22:25]
	v_mfma_f32_16x16x32_bf16 v[18:21], v[202:205], v[226:229], v[18:21]
	v_mfma_f32_16x16x32_bf16 v[6:9], v[182:185], v[234:237], v[6:9]
	v_mfma_f32_16x16x32_bf16 v[2:5], v[202:205], v[234:237], v[2:5]
	s_setprio 0
	s_barrier
	s_add_i32 s66, s66, 2
	s_add_u32 s12, s12, 0x100
	s_addc_u32 s13, s13, 0
	s_add_u32 s64, s64, 0x100
	s_addc_u32 s65, s65, 0
	s_cmp_gt_u32 s66, 13
	s_cbranch_scc0 .LBB0_1016
	v_lshl_add_u32 v160, s10, 8, v146
	v_ashrrev_i32_e32 v161, 31, v160
	v_lshl_or_b32 v162, s8, 8, v148
	v_ashrrev_i32_e32 v163, 31, v162
	v_lshlrev_b64 v[160:161], 10, v[160:161]
	v_lshl_add_u64 v[160:161], v[160:161], 0, v[162:163]
	v_lshl_add_u64 v[160:161], v[160:161], 1, s[86:87]
	global_load_dwordx4 v[178:181], v[160:161], off
	global_load_dwordx4 v[182:185], v[160:161], off offset:256
	s_mov_b64 vcc, 0x8000
	v_lshl_add_u64 v[162:163], v[160:161], 0, vcc
	global_load_dwordx4 v[186:189], v[162:163], off
	global_load_dwordx4 v[202:205], v[162:163], off offset:256
	s_mov_b64 vcc, 0x10000
	v_lshl_add_u64 v[162:163], v[160:161], 0, vcc
	global_load_dwordx4 v[206:209], v[162:163], off
	global_load_dwordx4 v[210:213], v[162:163], off offset:256
	s_mov_b64 vcc, 0x18000
	v_lshl_add_u64 v[162:163], v[160:161], 0, vcc
	global_load_dwordx4 v[214:217], v[162:163], off
	global_load_dwordx4 v[218:221], v[162:163], off offset:256
	s_mov_b64 vcc, 0x40000
	v_lshl_add_u64 v[162:163], v[160:161], 0, vcc
	global_load_dwordx4 v[222:225], v[162:163], off
	global_load_dwordx4 v[226:229], v[162:163], off offset:256
	s_mov_b64 vcc, 0x48000
	v_lshl_add_u64 v[162:163], v[160:161], 0, vcc
	global_load_dwordx4 v[230:233], v[162:163], off
	global_load_dwordx4 v[234:237], v[162:163], off offset:256
	s_and_b64 vcc, exec, s[46:47]
	s_cbranch_vccz .LBB0_1019
	s_barrier
; DI unsigned pk2(float lo, float hi) { return pg8::cvt_pk_bf16(lo, hi); }
; DI float bflo(unsigned w) { return __uint_as_float(w << 16); }
; DI float bfhi(unsigned w) { return __uint_as_float(w & 0xffff0000u); }
;     DI void operator()(const f32x4 (&acc)[2][2][4][2], const pg8::Unit& u, int wr, int wc, int fr, int fq) const {
;         const int row0 = u.pm * 256 + wr * 64 + fr, col0 = u.pn * 256 + wc * 32 + 8 * fq;
; #pragma unroll
;         for (int ai = 0; ai < 2; ++ai)
; #pragma unroll
;             for (int m = 0; m < 4; ++m) {
;                 const int row = row0 + ai * 128 + m * 16; float ss = 0.f;
; #pragma unroll
;                 for (int bj = 0; bj < 2; ++bj) {
;                     const size_t off = (size_t)row * DM + col0 + bj * 128;
;                     f32x4 b0, b1;
;                     if (base32) { b0 = *(const f32x4*)(base32 + off); b1 = *(const f32x4*)(base32 + off + 4); }
;                     else { const u32x4 bb = *(const u32x4*)(XB + off); b0 = (f32x4){bflo(bb.x), bfhi(bb.x), bflo(bb.y), bfhi(bb.y)}; b1 = (f32x4){bflo(bb.z), bfhi(bb.z), bflo(bb.w), bfhi(bb.w)}; }
;                     const f32x4 v0 = b0 + acc[ai][bj][m][0] * alpha, v1 = b1 + acc[ai][bj][m][1] * alpha;
;                     ss += ((v0[0] * v0[0] + v0[1] * v0[1]) + (v0[2] * v0[2] + v0[3] * v0[3])) + ((v1[0] * v1[0] + v1[1] * v1[1]) + (v1[2] * v1[2] + v1[3] * v1[3]));
;                     u32x4 w; w.x = pk2(v0[0], v0[1]); w.y = pk2(v0[2], v0[3]); w.z = pk2(v1[0], v1[1]); w.w = pk2(v1[2], v1[3]);
;                     *(u32x4*)(XB + off) = w;
;                 }
;                 ss += __shfl_xor(ss, 16); ss += __shfl_xor(ss, 32);
;                 if (fq == 0) ssq[(size_t)row * 16 + u.pn * 4 + wc] = ss;
;                 asm volatile("" ::: "memory");
.LBB0_1019:
	v_and_b32_e32 v144, 64, v194
	v_xor_b32_e32 v143, 16, v194
	v_add_u32_e32 v144, 64, v144
	v_cmp_lt_i32_e32 vcc, v143, v144
	v_lshl_add_u32 v142, s10, 8, v146
	v_lshl_or_b32 v140, s8, 8, v148
	v_cndmask_b32_e32 v143, v194, v143, vcc
	v_lshlrev_b32_e32 v151, 2, v143
	v_xor_b32_e32 v143, 32, v194
	v_cmp_lt_i32_e32 vcc, v143, v144
	v_ashrrev_i32_e32 v141, 31, v140
	s_lshl_b32 s38, s8, 2
	v_cndmask_b32_e32 v143, v194, v143, vcc
	v_lshlrev_b32_e32 v150, 2, v143
	v_ashrrev_i32_e32 v143, 31, v142
	v_lshlrev_b64 v[144:145], 10, v[142:143]
	v_lshl_add_u64 v[144:145], v[144:145], 0, v[140:141]
	v_lshl_add_u64 v[144:145], v[144:145], 1, s[86:87]
	s_ashr_i32 s39, s38, 31
	s_waitcnt vmcnt(11)
	s_nop 1
	v_mov_b32_e32 v152, v178
	v_mov_b32_e32 v153, v179
	v_mov_b32_e32 v154, v180
	v_mov_b32_e32 v155, v181
	v_lshlrev_b32_e32 v156, 16, v152
	v_and_b32_e32 v157, 0xffff0000, v152
	v_lshlrev_b32_e32 v152, 16, v153
	v_and_b32_e32 v153, 0xffff0000, v153
	v_lshlrev_b32_e32 v158, 16, v154
	v_and_b32_e32 v159, 0xffff0000, v154
	v_lshlrev_b32_e32 v154, 16, v155
	v_and_b32_e32 v155, 0xffff0000, v155
	v_pk_add_f32 v[128:129], v[128:129], v[152:153]
	v_pk_add_f32 v[126:127], v[126:127], v[156:157]
	v_pk_add_f32 v[152:153], v[124:125], v[154:155]
	v_pk_add_f32 v[124:125], v[122:123], v[158:159]
	v_mul_f32_e32 v122, v127, v127
	v_mul_f32_e32 v123, v129, v129
	v_fmac_f32_e32 v122, v126, v126
	v_fmac_f32_e32 v123, v128, v128
	v_add_f32_e32 v122, v122, v123
	v_mul_f32_e32 v123, v125, v125
	v_mul_f32_e32 v154, v153, v153
	v_fmac_f32_e32 v123, v124, v124
	v_fmac_f32_e32 v154, v152, v152
	v_add_f32_e32 v123, v123, v154
	v_add_f32_e32 v154, v122, v123
	v_cvt_pk_bf16_f32 v122, v126, v127
	v_cvt_pk_bf16_f32 v123, v128, v129
	v_cvt_pk_bf16_f32 v124, v124, v125
	v_cvt_pk_bf16_f32 v125, v152, v153
	global_store_dwordx4 v[144:145], v[122:125], off
	s_waitcnt vmcnt(11)
	s_nop 1
	v_mov_b32_e32 v122, v182
	v_mov_b32_e32 v123, v183
	v_mov_b32_e32 v124, v184
	v_mov_b32_e32 v125, v185
	v_lshlrev_b32_e32 v126, 16, v122
	v_and_b32_e32 v127, 0xffff0000, v122
	v_lshlrev_b32_e32 v122, 16, v123
	v_and_b32_e32 v123, 0xffff0000, v123
	v_lshlrev_b32_e32 v128, 16, v124
	v_and_b32_e32 v129, 0xffff0000, v124
	v_lshlrev_b32_e32 v124, 16, v125
	v_and_b32_e32 v125, 0xffff0000, v125
	v_pk_add_f32 v[120:121], v[120:121], v[122:123]
	v_pk_add_f32 v[118:119], v[118:119], v[126:127]
	v_pk_add_f32 v[122:123], v[116:117], v[124:125]
	v_pk_add_f32 v[116:117], v[114:115], v[128:129]
	v_mul_f32_e32 v114, v119, v119
	v_mul_f32_e32 v115, v121, v121
	v_fmac_f32_e32 v114, v118, v118
	v_fmac_f32_e32 v115, v120, v120
	v_add_f32_e32 v114, v114, v115
	v_mul_f32_e32 v115, v117, v117
	v_mul_f32_e32 v124, v123, v123
	v_fmac_f32_e32 v115, v116, v116
	v_fmac_f32_e32 v124, v122, v122
	v_add_f32_e32 v115, v115, v124
	v_add_f32_e32 v114, v114, v115
	v_add_f32_e32 v124, v154, v114
	v_cvt_pk_bf16_f32 v114, v118, v119
	v_cvt_pk_bf16_f32 v115, v120, v121
	v_cvt_pk_bf16_f32 v116, v116, v117
	v_cvt_pk_bf16_f32 v117, v122, v123
	global_store_dwordx4 v[144:145], v[114:117], off offset:256
	ds_bpermute_b32 v114, v151, v124
	s_waitcnt lgkmcnt(0)
	v_add_f32_e32 v114, v124, v114
	ds_bpermute_b32 v115, v150, v114
	s_and_saveexec_b64 s[12:13], s[42:43]
	v_lshlrev_b64 v[116:117], 6, v[142:143]
	v_lshl_add_u64 v[116:117], s[88:89], 0, v[116:117]
	v_lshl_add_u64 v[116:117], s[38:39], 2, v[116:117]
	s_lshl_b32 s8, s60, 2
	v_lshl_add_u64 v[116:117], v[116:117], 0, s[8:9]
	s_waitcnt lgkmcnt(0)
	v_add_f32_e32 v114, v114, v115
	global_store_dword v[116:117], v114, off
.LBB0_1021:
	s_or_b64 exec, exec, s[12:13]
	s_mov_b64 vcc, 0x50000
	v_lshl_add_u64 v[162:163], v[160:161], 0, vcc
	global_load_dwordx4 v[178:181], v[162:163], off
	global_load_dwordx4 v[182:185], v[162:163], off offset:256
	v_or_b32_e32 v114, 16, v142
	s_waitcnt lgkmcnt(0)
	v_ashrrev_i32_e32 v115, 31, v114
	v_lshlrev_b64 v[116:117], 10, v[114:115]
	v_lshl_add_u64 v[116:117], v[116:117], 0, v[140:141]
	v_lshl_add_u64 v[116:117], v[116:117], 1, s[86:87]
	s_waitcnt vmcnt(14)
	s_nop 1
	v_mov_b32_e32 v118, v186
	v_mov_b32_e32 v119, v187
	v_mov_b32_e32 v120, v188
	v_mov_b32_e32 v121, v189
	v_lshlrev_b32_e32 v122, 16, v118
	v_and_b32_e32 v123, 0xffff0000, v118
	v_lshlrev_b32_e32 v118, 16, v119
	v_and_b32_e32 v119, 0xffff0000, v119
	v_lshlrev_b32_e32 v124, 16, v120
	v_and_b32_e32 v125, 0xffff0000, v120
	v_lshlrev_b32_e32 v120, 16, v121
	v_and_b32_e32 v121, 0xffff0000, v121
	v_pk_add_f32 v[112:113], v[112:113], v[118:119]
	v_pk_add_f32 v[110:111], v[110:111], v[122:123]
	v_pk_add_f32 v[118:119], v[108:109], v[120:121]
	v_pk_add_f32 v[108:109], v[106:107], v[124:125]
	v_mul_f32_e32 v106, v111, v111
	v_mul_f32_e32 v107, v113, v113
	v_fmac_f32_e32 v106, v110, v110
	v_fmac_f32_e32 v107, v112, v112
	v_add_f32_e32 v106, v106, v107
	v_mul_f32_e32 v107, v109, v109
	v_mul_f32_e32 v120, v119, v119
	v_fmac_f32_e32 v107, v108, v108
	v_fmac_f32_e32 v120, v118, v118
	v_add_f32_e32 v107, v107, v120
	v_add_f32_e32 v120, v106, v107
	v_cvt_pk_bf16_f32 v106, v110, v111
	v_cvt_pk_bf16_f32 v107, v112, v113
	v_cvt_pk_bf16_f32 v108, v108, v109
	v_cvt_pk_bf16_f32 v109, v118, v119
	global_store_dwordx4 v[116:117], v[106:109], off
	s_waitcnt vmcnt(14)
	s_nop 1
	v_mov_b32_e32 v106, v202
	v_mov_b32_e32 v107, v203
	v_mov_b32_e32 v108, v204
	v_mov_b32_e32 v109, v205
	v_lshlrev_b32_e32 v110, 16, v106
	v_and_b32_e32 v111, 0xffff0000, v106
	v_lshlrev_b32_e32 v106, 16, v107
	v_and_b32_e32 v107, 0xffff0000, v107
	v_lshlrev_b32_e32 v112, 16, v108
	v_and_b32_e32 v113, 0xffff0000, v108
	v_lshlrev_b32_e32 v108, 16, v109
	v_and_b32_e32 v109, 0xffff0000, v109
	v_pk_add_f32 v[104:105], v[104:105], v[106:107]
	v_pk_add_f32 v[102:103], v[102:103], v[110:111]
	v_pk_add_f32 v[106:107], v[100:101], v[108:109]
	v_pk_add_f32 v[100:101], v[98:99], v[112:113]
	v_mul_f32_e32 v98, v103, v103
	v_mul_f32_e32 v99, v105, v105
	v_fmac_f32_e32 v98, v102, v102
	v_fmac_f32_e32 v99, v104, v104
	v_add_f32_e32 v98, v98, v99
	v_mul_f32_e32 v99, v101, v101
	v_mul_f32_e32 v108, v107, v107
	v_fmac_f32_e32 v99, v100, v100
	v_fmac_f32_e32 v108, v106, v106
	v_add_f32_e32 v99, v99, v108
	v_add_f32_e32 v98, v98, v99
	v_add_f32_e32 v108, v120, v98
	v_cvt_pk_bf16_f32 v98, v102, v103
	v_cvt_pk_bf16_f32 v99, v104, v105
	v_cvt_pk_bf16_f32 v100, v100, v101
	v_cvt_pk_bf16_f32 v101, v106, v107
	global_store_dwordx4 v[116:117], v[98:101], off offset:256
	ds_bpermute_b32 v98, v151, v108
	s_waitcnt lgkmcnt(0)
	v_add_f32_e32 v98, v108, v98
	ds_bpermute_b32 v99, v150, v98
	s_and_saveexec_b64 s[12:13], s[42:43]
	v_lshlrev_b64 v[100:101], 6, v[114:115]
	v_lshl_add_u64 v[100:101], s[88:89], 0, v[100:101]
	v_lshl_add_u64 v[100:101], s[38:39], 2, v[100:101]
	s_lshl_b32 s8, s60, 2
	v_lshl_add_u64 v[100:101], v[100:101], 0, s[8:9]
	s_waitcnt lgkmcnt(0)
	v_add_f32_e32 v98, v98, v99
	global_store_dword v[100:101], v98, off
; DI unsigned pk2(float lo, float hi) { return pg8::cvt_pk_bf16(lo, hi); }
; DI float bflo(unsigned w) { return __uint_as_float(w << 16); }
; DI float bfhi(unsigned w) { return __uint_as_float(w & 0xffff0000u); }
;     DI void operator()(const f32x4 (&acc)[2][2][4][2], const pg8::Unit& u, int wr, int wc, int fr, int fq) const {
;     ...
;         for (int ai = 0; ai < 2; ++ai)
; #pragma unroll
;             for (int m = 0; m < 4; ++m) {
;                 const int row = row0 + ai * 128 + m * 16; float ss = 0.f;
; #pragma unroll
;                 for (int bj = 0; bj < 2; ++bj) {
;                     const size_t off = (size_t)row * DM + col0 + bj * 128;
;                     f32x4 b0, b1;
;                     if (base32) { b0 = *(const f32x4*)(base32 + off); b1 = *(const f32x4*)(base32 + off + 4); }
;                     else { const u32x4 bb = *(const u32x4*)(XB + off); b0 = (f32x4){bflo(bb.x), bfhi(bb.x), bflo(bb.y), bfhi(bb.y)}; b1 = (f32x4){bflo(bb.z), bfhi(bb.z), bflo(bb.w), bfhi(bb.w)}; }
;                     const f32x4 v0 = b0 + acc[ai][bj][m][0] * alpha, v1 = b1 + acc[ai][bj][m][1] * alpha;
;                     ss += ((v0[0] * v0[0] + v0[1] * v0[1]) + (v0[2] * v0[2] + v0[3] * v0[3])) + ((v1[0] * v1[0] + v1[1] * v1[1]) + (v1[2] * v1[2] + v1[3] * v1[3]));
;                     u32x4 w; w.x = pk2(v0[0], v0[1]); w.y = pk2(v0[2], v0[3]); w.z = pk2(v1[0], v1[1]); w.w = pk2(v1[2], v1[3]);
;                     *(u32x4*)(XB + off) = w;
;                 }
;                 ss += __shfl_xor(ss, 16); ss += __shfl_xor(ss, 32);
;                 if (fq == 0) ssq[(size_t)row * 16 + u.pn * 4 + wc] = ss;
;                 asm volatile("" ::: "memory");
;             }
.LBB0_1023:
	s_or_b64 exec, exec, s[12:13]
	s_mov_b64 vcc, 0x58000
	v_lshl_add_u64 v[162:163], v[160:161], 0, vcc
	global_load_dwordx4 v[186:189], v[162:163], off
	global_load_dwordx4 v[202:205], v[162:163], off offset:256
	v_or_b32_e32 v98, 32, v142
	s_waitcnt lgkmcnt(0)
	v_ashrrev_i32_e32 v99, 31, v98
	v_lshlrev_b64 v[100:101], 10, v[98:99]
	v_lshl_add_u64 v[100:101], v[100:101], 0, v[140:141]
	v_lshl_add_u64 v[100:101], v[100:101], 1, s[86:87]
	s_waitcnt vmcnt(17)
	s_nop 1
	v_mov_b32_e32 v102, v206
	v_mov_b32_e32 v103, v207
	v_mov_b32_e32 v104, v208
	v_mov_b32_e32 v105, v209
	v_lshlrev_b32_e32 v106, 16, v102
	v_and_b32_e32 v107, 0xffff0000, v102
	v_lshlrev_b32_e32 v102, 16, v103
	v_and_b32_e32 v103, 0xffff0000, v103
	v_lshlrev_b32_e32 v108, 16, v104
	v_and_b32_e32 v109, 0xffff0000, v104
	v_lshlrev_b32_e32 v104, 16, v105
	v_and_b32_e32 v105, 0xffff0000, v105
	v_pk_add_f32 v[96:97], v[96:97], v[102:103]
	v_pk_add_f32 v[94:95], v[94:95], v[106:107]
	v_pk_add_f32 v[102:103], v[92:93], v[104:105]
	v_pk_add_f32 v[92:93], v[90:91], v[108:109]
	v_mul_f32_e32 v90, v95, v95
	v_mul_f32_e32 v91, v97, v97
	v_fmac_f32_e32 v90, v94, v94
	v_fmac_f32_e32 v91, v96, v96
	v_add_f32_e32 v90, v90, v91
	v_mul_f32_e32 v91, v93, v93
	v_mul_f32_e32 v104, v103, v103
	v_fmac_f32_e32 v91, v92, v92
	v_fmac_f32_e32 v104, v102, v102
	v_add_f32_e32 v91, v91, v104
	v_add_f32_e32 v104, v90, v91
	v_cvt_pk_bf16_f32 v90, v94, v95
	v_cvt_pk_bf16_f32 v91, v96, v97
	v_cvt_pk_bf16_f32 v92, v92, v93
	v_cvt_pk_bf16_f32 v93, v102, v103
	global_store_dwordx4 v[100:101], v[90:93], off
	s_waitcnt vmcnt(17)
	s_nop 1
	v_mov_b32_e32 v90, v210
	v_mov_b32_e32 v91, v211
	v_mov_b32_e32 v92, v212
	v_mov_b32_e32 v93, v213
	v_lshlrev_b32_e32 v94, 16, v90
	v_and_b32_e32 v95, 0xffff0000, v90
	v_lshlrev_b32_e32 v90, 16, v91
	v_and_b32_e32 v91, 0xffff0000, v91
	v_lshlrev_b32_e32 v96, 16, v92
	v_and_b32_e32 v97, 0xffff0000, v92
	v_lshlrev_b32_e32 v92, 16, v93
	v_and_b32_e32 v93, 0xffff0000, v93
	v_pk_add_f32 v[88:89], v[88:89], v[90:91]
	v_pk_add_f32 v[86:87], v[86:87], v[94:95]
	v_pk_add_f32 v[90:91], v[84:85], v[92:93]
	v_pk_add_f32 v[84:85], v[82:83], v[96:97]
	v_mul_f32_e32 v82, v87, v87
	v_mul_f32_e32 v83, v89, v89
	v_fmac_f32_e32 v82, v86, v86
	v_fmac_f32_e32 v83, v88, v88
	v_add_f32_e32 v82, v82, v83
	v_mul_f32_e32 v83, v85, v85
	v_mul_f32_e32 v92, v91, v91
	v_fmac_f32_e32 v83, v84, v84
	v_fmac_f32_e32 v92, v90, v90
	v_add_f32_e32 v83, v83, v92
	v_add_f32_e32 v82, v82, v83
	v_add_f32_e32 v92, v104, v82
	v_cvt_pk_bf16_f32 v82, v86, v87
	v_cvt_pk_bf16_f32 v83, v88, v89
	v_cvt_pk_bf16_f32 v84, v84, v85
	v_cvt_pk_bf16_f32 v85, v90, v91
	global_store_dwordx4 v[100:101], v[82:85], off offset:256
	ds_bpermute_b32 v82, v151, v92
	s_waitcnt lgkmcnt(0)
	v_add_f32_e32 v82, v92, v82
	ds_bpermute_b32 v83, v150, v82
	s_and_saveexec_b64 s[12:13], s[42:43]
	v_lshlrev_b64 v[84:85], 6, v[98:99]
	v_lshl_add_u64 v[84:85], s[88:89], 0, v[84:85]
	v_lshl_add_u64 v[84:85], s[38:39], 2, v[84:85]
	s_lshl_b32 s8, s60, 2
	v_lshl_add_u64 v[84:85], v[84:85], 0, s[8:9]
	s_waitcnt lgkmcnt(0)
	v_add_f32_e32 v82, v82, v83
	global_store_dword v[84:85], v82, off
.LBB0_1025:
	s_or_b64 exec, exec, s[12:13]
	v_or_b32_e32 v82, 48, v142
	s_waitcnt lgkmcnt(0)
	v_ashrrev_i32_e32 v83, 31, v82
	v_lshlrev_b64 v[84:85], 10, v[82:83]
	v_lshl_add_u64 v[84:85], v[84:85], 0, v[140:141]
	v_lshl_add_u64 v[84:85], v[84:85], 1, s[86:87]
	s_waitcnt vmcnt(18)
	s_nop 1
	v_mov_b32_e32 v86, v214
	v_mov_b32_e32 v87, v215
	v_mov_b32_e32 v88, v216
	v_mov_b32_e32 v89, v217
	v_lshlrev_b32_e32 v90, 16, v86
	v_and_b32_e32 v91, 0xffff0000, v86
	v_lshlrev_b32_e32 v86, 16, v87
	v_and_b32_e32 v87, 0xffff0000, v87
	v_lshlrev_b32_e32 v92, 16, v88
	v_and_b32_e32 v93, 0xffff0000, v88
	v_lshlrev_b32_e32 v88, 16, v89
	v_and_b32_e32 v89, 0xffff0000, v89
	v_pk_add_f32 v[80:81], v[80:81], v[86:87]
	v_pk_add_f32 v[78:79], v[78:79], v[90:91]
	v_pk_add_f32 v[86:87], v[76:77], v[88:89]
	v_pk_add_f32 v[76:77], v[74:75], v[92:93]
	v_mul_f32_e32 v74, v79, v79
	v_mul_f32_e32 v75, v81, v81
	v_fmac_f32_e32 v74, v78, v78
	v_fmac_f32_e32 v75, v80, v80
	v_add_f32_e32 v74, v74, v75
	v_mul_f32_e32 v75, v77, v77
	v_mul_f32_e32 v88, v87, v87
	v_fmac_f32_e32 v75, v76, v76
	v_fmac_f32_e32 v88, v86, v86
	v_add_f32_e32 v75, v75, v88
	v_add_f32_e32 v88, v74, v75
	v_cvt_pk_bf16_f32 v74, v78, v79
	v_cvt_pk_bf16_f32 v75, v80, v81
	v_cvt_pk_bf16_f32 v76, v76, v77
	v_cvt_pk_bf16_f32 v77, v86, v87
	global_store_dwordx4 v[84:85], v[74:77], off
	s_waitcnt vmcnt(18)
	s_nop 1
	v_mov_b32_e32 v74, v218
	v_mov_b32_e32 v75, v219
	v_mov_b32_e32 v76, v220
	v_mov_b32_e32 v77, v221
	v_lshlrev_b32_e32 v78, 16, v74
	v_and_b32_e32 v79, 0xffff0000, v74
	v_lshlrev_b32_e32 v74, 16, v75
	v_and_b32_e32 v75, 0xffff0000, v75
	v_lshlrev_b32_e32 v80, 16, v76
	v_and_b32_e32 v81, 0xffff0000, v76
	v_lshlrev_b32_e32 v76, 16, v77
	v_and_b32_e32 v77, 0xffff0000, v77
	v_pk_add_f32 v[72:73], v[72:73], v[74:75]
	v_pk_add_f32 v[70:71], v[70:71], v[78:79]
	v_pk_add_f32 v[74:75], v[68:69], v[76:77]
	v_pk_add_f32 v[68:69], v[66:67], v[80:81]
	v_mul_f32_e32 v66, v71, v71
	v_mul_f32_e32 v67, v73, v73
	v_fmac_f32_e32 v66, v70, v70
	v_fmac_f32_e32 v67, v72, v72
	v_add_f32_e32 v66, v66, v67
	v_mul_f32_e32 v67, v69, v69
	v_mul_f32_e32 v76, v75, v75
	v_fmac_f32_e32 v67, v68, v68
	v_fmac_f32_e32 v76, v74, v74
	v_add_f32_e32 v67, v67, v76
	v_add_f32_e32 v66, v66, v67
	v_add_f32_e32 v76, v88, v66
	v_cvt_pk_bf16_f32 v66, v70, v71
	v_cvt_pk_bf16_f32 v67, v72, v73
	v_cvt_pk_bf16_f32 v68, v68, v69
	v_cvt_pk_bf16_f32 v69, v74, v75
	global_store_dwordx4 v[84:85], v[66:69], off offset:256
	ds_bpermute_b32 v66, v151, v76
	s_waitcnt lgkmcnt(0)
	v_add_f32_e32 v66, v76, v66
	ds_bpermute_b32 v67, v150, v66
	s_and_saveexec_b64 s[12:13], s[42:43]
	v_lshlrev_b64 v[68:69], 6, v[82:83]
	v_lshl_add_u64 v[68:69], s[88:89], 0, v[68:69]
	v_lshl_add_u64 v[68:69], s[38:39], 2, v[68:69]
	s_lshl_b32 s8, s60, 2
	v_lshl_add_u64 v[68:69], v[68:69], 0, s[8:9]
	s_waitcnt lgkmcnt(0)
	v_add_f32_e32 v66, v66, v67
	global_store_dword v[68:69], v66, off
; DI unsigned pk2(float lo, float hi) { return pg8::cvt_pk_bf16(lo, hi); }
; DI float bflo(unsigned w) { return __uint_as_float(w << 16); }
; DI float bfhi(unsigned w) { return __uint_as_float(w & 0xffff0000u); }
;     DI void operator()(const f32x4 (&acc)[2][2][4][2], const pg8::Unit& u, int wr, int wc, int fr, int fq) const {
;     ...
;         for (int ai = 0; ai < 2; ++ai)
; #pragma unroll
;             for (int m = 0; m < 4; ++m) {
;                 const int row = row0 + ai * 128 + m * 16; float ss = 0.f;
; #pragma unroll
;                 for (int bj = 0; bj < 2; ++bj) {
;                     const size_t off = (size_t)row * DM + col0 + bj * 128;
;                     f32x4 b0, b1;
;                     if (base32) { b0 = *(const f32x4*)(base32 + off); b1 = *(const f32x4*)(base32 + off + 4); }
;                     else { const u32x4 bb = *(const u32x4*)(XB + off); b0 = (f32x4){bflo(bb.x), bfhi(bb.x), bflo(bb.y), bfhi(bb.y)}; b1 = (f32x4){bflo(bb.z), bfhi(bb.z), bflo(bb.w), bfhi(bb.w)}; }
;                     const f32x4 v0 = b0 + acc[ai][bj][m][0] * alpha, v1 = b1 + acc[ai][bj][m][1] * alpha;
;                     ss += ((v0[0] * v0[0] + v0[1] * v0[1]) + (v0[2] * v0[2] + v0[3] * v0[3])) + ((v1[0] * v1[0] + v1[1] * v1[1]) + (v1[2] * v1[2] + v1[3] * v1[3]));
;                     u32x4 w; w.x = pk2(v0[0], v0[1]); w.y = pk2(v0[2], v0[3]); w.z = pk2(v1[0], v1[1]); w.w = pk2(v1[2], v1[3]);
;                     *(u32x4*)(XB + off) = w;
;                 }
;                 ss += __shfl_xor(ss, 16); ss += __shfl_xor(ss, 32);
;                 if (fq == 0) ssq[(size_t)row * 16 + u.pn * 4 + wc] = ss;
;                 asm volatile("" ::: "memory");
;             }
.LBB0_1027:
	s_or_b64 exec, exec, s[12:13]
	v_add_u32_e32 v66, 0x80, v142
	s_waitcnt lgkmcnt(0)
	v_ashrrev_i32_e32 v67, 31, v66
	v_lshlrev_b64 v[68:69], 10, v[66:67]
	v_lshl_add_u64 v[68:69], v[68:69], 0, v[140:141]
	v_lshl_add_u64 v[68:69], v[68:69], 1, s[86:87]
	s_waitcnt vmcnt(19)
	s_nop 1
	v_mov_b32_e32 v70, v222
	v_mov_b32_e32 v71, v223
	v_mov_b32_e32 v72, v224
	v_mov_b32_e32 v73, v225
	v_lshlrev_b32_e32 v74, 16, v70
	v_and_b32_e32 v75, 0xffff0000, v70
	v_lshlrev_b32_e32 v70, 16, v71
	v_and_b32_e32 v71, 0xffff0000, v71
	v_lshlrev_b32_e32 v76, 16, v72
	v_and_b32_e32 v77, 0xffff0000, v72
	v_lshlrev_b32_e32 v72, 16, v73
	v_and_b32_e32 v73, 0xffff0000, v73
	v_pk_add_f32 v[64:65], v[64:65], v[70:71]
	v_pk_add_f32 v[62:63], v[62:63], v[74:75]
	v_pk_add_f32 v[70:71], v[60:61], v[72:73]
	v_pk_add_f32 v[60:61], v[58:59], v[76:77]
	v_mul_f32_e32 v58, v63, v63
	v_mul_f32_e32 v59, v65, v65
	v_fmac_f32_e32 v58, v62, v62
	v_fmac_f32_e32 v59, v64, v64
	v_add_f32_e32 v58, v58, v59
	v_mul_f32_e32 v59, v61, v61
	v_mul_f32_e32 v72, v71, v71
	v_fmac_f32_e32 v59, v60, v60
	v_fmac_f32_e32 v72, v70, v70
	v_add_f32_e32 v59, v59, v72
	v_add_f32_e32 v72, v58, v59
	v_cvt_pk_bf16_f32 v58, v62, v63
	v_cvt_pk_bf16_f32 v59, v64, v65
	v_cvt_pk_bf16_f32 v60, v60, v61
	v_cvt_pk_bf16_f32 v61, v70, v71
	global_store_dwordx4 v[68:69], v[58:61], off
	s_waitcnt vmcnt(19)
	s_nop 1
	v_mov_b32_e32 v58, v226
	v_mov_b32_e32 v59, v227
	v_mov_b32_e32 v60, v228
	v_mov_b32_e32 v61, v229
	v_lshlrev_b32_e32 v62, 16, v58
	v_and_b32_e32 v63, 0xffff0000, v58
	v_lshlrev_b32_e32 v58, 16, v59
	v_and_b32_e32 v59, 0xffff0000, v59
	v_lshlrev_b32_e32 v64, 16, v60
	v_and_b32_e32 v65, 0xffff0000, v60
	v_lshlrev_b32_e32 v60, 16, v61
	v_and_b32_e32 v61, 0xffff0000, v61
	v_pk_add_f32 v[56:57], v[56:57], v[58:59]
	v_pk_add_f32 v[54:55], v[54:55], v[62:63]
	v_pk_add_f32 v[58:59], v[52:53], v[60:61]
	v_pk_add_f32 v[52:53], v[50:51], v[64:65]
	v_mul_f32_e32 v50, v55, v55
	v_mul_f32_e32 v51, v57, v57
	v_fmac_f32_e32 v50, v54, v54
	v_fmac_f32_e32 v51, v56, v56
	v_add_f32_e32 v50, v50, v51
	v_mul_f32_e32 v51, v53, v53
	v_mul_f32_e32 v60, v59, v59
	v_fmac_f32_e32 v51, v52, v52
	v_fmac_f32_e32 v60, v58, v58
	v_add_f32_e32 v51, v51, v60
	v_add_f32_e32 v50, v50, v51
	v_add_f32_e32 v60, v72, v50
	v_cvt_pk_bf16_f32 v50, v54, v55
	v_cvt_pk_bf16_f32 v51, v56, v57
	v_cvt_pk_bf16_f32 v52, v52, v53
	v_cvt_pk_bf16_f32 v53, v58, v59
	global_store_dwordx4 v[68:69], v[50:53], off offset:256
	ds_bpermute_b32 v50, v151, v60
	s_waitcnt lgkmcnt(0)
	v_add_f32_e32 v50, v60, v50
	ds_bpermute_b32 v51, v150, v50
	s_and_saveexec_b64 s[12:13], s[42:43]
	v_lshlrev_b64 v[52:53], 6, v[66:67]
	v_lshl_add_u64 v[52:53], s[88:89], 0, v[52:53]
	v_lshl_add_u64 v[52:53], s[38:39], 2, v[52:53]
	s_lshl_b32 s8, s60, 2
	v_lshl_add_u64 v[52:53], v[52:53], 0, s[8:9]
	s_waitcnt lgkmcnt(0)
	v_add_f32_e32 v50, v50, v51
	global_store_dword v[52:53], v50, off
.LBB0_1029:
	s_or_b64 exec, exec, s[12:13]
	v_add_u32_e32 v50, 0x90, v142
	s_waitcnt lgkmcnt(0)
	v_ashrrev_i32_e32 v51, 31, v50
	v_lshlrev_b64 v[52:53], 10, v[50:51]
	v_lshl_add_u64 v[52:53], v[52:53], 0, v[140:141]
	v_lshl_add_u64 v[52:53], v[52:53], 1, s[86:87]
	s_waitcnt vmcnt(20)
	s_nop 1
	v_mov_b32_e32 v54, v230
	v_mov_b32_e32 v55, v231
	v_mov_b32_e32 v56, v232
	v_mov_b32_e32 v57, v233
	v_lshlrev_b32_e32 v58, 16, v54
	v_and_b32_e32 v59, 0xffff0000, v54
	v_lshlrev_b32_e32 v54, 16, v55
	v_and_b32_e32 v55, 0xffff0000, v55
	v_lshlrev_b32_e32 v60, 16, v56
	v_and_b32_e32 v61, 0xffff0000, v56
	v_lshlrev_b32_e32 v56, 16, v57
	v_and_b32_e32 v57, 0xffff0000, v57
	v_pk_add_f32 v[48:49], v[48:49], v[54:55]
	v_pk_add_f32 v[46:47], v[46:47], v[58:59]
	v_pk_add_f32 v[54:55], v[44:45], v[56:57]
	v_pk_add_f32 v[44:45], v[42:43], v[60:61]
	v_mul_f32_e32 v42, v47, v47
	v_mul_f32_e32 v43, v49, v49
	v_fmac_f32_e32 v42, v46, v46
	v_fmac_f32_e32 v43, v48, v48
	v_add_f32_e32 v42, v42, v43
	v_mul_f32_e32 v43, v45, v45
	v_mul_f32_e32 v56, v55, v55
	v_fmac_f32_e32 v43, v44, v44
	v_fmac_f32_e32 v56, v54, v54
	v_add_f32_e32 v43, v43, v56
	v_add_f32_e32 v56, v42, v43
	v_cvt_pk_bf16_f32 v42, v46, v47
	v_cvt_pk_bf16_f32 v43, v48, v49
	v_cvt_pk_bf16_f32 v44, v44, v45
	v_cvt_pk_bf16_f32 v45, v54, v55
	global_store_dwordx4 v[52:53], v[42:45], off
	s_waitcnt vmcnt(20)
	s_nop 1
	v_mov_b32_e32 v42, v234
	v_mov_b32_e32 v43, v235
	v_mov_b32_e32 v44, v236
	v_mov_b32_e32 v45, v237
	v_lshlrev_b32_e32 v46, 16, v42
	v_and_b32_e32 v47, 0xffff0000, v42
	v_lshlrev_b32_e32 v42, 16, v43
	v_and_b32_e32 v43, 0xffff0000, v43
	v_lshlrev_b32_e32 v48, 16, v44
	v_and_b32_e32 v49, 0xffff0000, v44
	v_lshlrev_b32_e32 v44, 16, v45
	v_and_b32_e32 v45, 0xffff0000, v45
	v_pk_add_f32 v[40:41], v[40:41], v[42:43]
	v_pk_add_f32 v[38:39], v[38:39], v[46:47]
	v_pk_add_f32 v[42:43], v[36:37], v[44:45]
	v_pk_add_f32 v[36:37], v[34:35], v[48:49]
	v_mul_f32_e32 v34, v39, v39
	v_mul_f32_e32 v35, v41, v41
	v_fmac_f32_e32 v34, v38, v38
	v_fmac_f32_e32 v35, v40, v40
	v_add_f32_e32 v34, v34, v35
	v_mul_f32_e32 v35, v37, v37
	v_mul_f32_e32 v44, v43, v43
	v_fmac_f32_e32 v35, v36, v36
	v_fmac_f32_e32 v44, v42, v42
	v_add_f32_e32 v35, v35, v44
	v_add_f32_e32 v34, v34, v35
	v_add_f32_e32 v44, v56, v34
	v_cvt_pk_bf16_f32 v34, v38, v39
	v_cvt_pk_bf16_f32 v35, v40, v41
	v_cvt_pk_bf16_f32 v36, v36, v37
	v_cvt_pk_bf16_f32 v37, v42, v43
	global_store_dwordx4 v[52:53], v[34:37], off offset:256
	ds_bpermute_b32 v34, v151, v44
	s_waitcnt lgkmcnt(0)
	v_add_f32_e32 v34, v44, v34
	ds_bpermute_b32 v35, v150, v34
	s_and_saveexec_b64 s[12:13], s[42:43]
	v_lshlrev_b64 v[36:37], 6, v[50:51]
	v_lshl_add_u64 v[36:37], s[88:89], 0, v[36:37]
	v_lshl_add_u64 v[36:37], s[38:39], 2, v[36:37]
	s_lshl_b32 s8, s60, 2
	v_lshl_add_u64 v[36:37], v[36:37], 0, s[8:9]
	s_waitcnt lgkmcnt(0)
	v_add_f32_e32 v34, v34, v35
	global_store_dword v[36:37], v34, off
; DI unsigned pk2(float lo, float hi) { return pg8::cvt_pk_bf16(lo, hi); }
; DI float bflo(unsigned w) { return __uint_as_float(w << 16); }
; DI float bfhi(unsigned w) { return __uint_as_float(w & 0xffff0000u); }
;     DI void operator()(const f32x4 (&acc)[2][2][4][2], const pg8::Unit& u, int wr, int wc, int fr, int fq) const {
;     ...
;         for (int ai = 0; ai < 2; ++ai)
; #pragma unroll
;             for (int m = 0; m < 4; ++m) {
;                 const int row = row0 + ai * 128 + m * 16; float ss = 0.f;
; #pragma unroll
;                 for (int bj = 0; bj < 2; ++bj) {
;                     const size_t off = (size_t)row * DM + col0 + bj * 128;
;                     f32x4 b0, b1;
;                     if (base32) { b0 = *(const f32x4*)(base32 + off); b1 = *(const f32x4*)(base32 + off + 4); }
;                     else { const u32x4 bb = *(const u32x4*)(XB + off); b0 = (f32x4){bflo(bb.x), bfhi(bb.x), bflo(bb.y), bfhi(bb.y)}; b1 = (f32x4){bflo(bb.z), bfhi(bb.z), bflo(bb.w), bfhi(bb.w)}; }
;                     const f32x4 v0 = b0 + acc[ai][bj][m][0] * alpha, v1 = b1 + acc[ai][bj][m][1] * alpha;
;                     ss += ((v0[0] * v0[0] + v0[1] * v0[1]) + (v0[2] * v0[2] + v0[3] * v0[3])) + ((v1[0] * v1[0] + v1[1] * v1[1]) + (v1[2] * v1[2] + v1[3] * v1[3]));
;                     u32x4 w; w.x = pk2(v0[0], v0[1]); w.y = pk2(v0[2], v0[3]); w.z = pk2(v1[0], v1[1]); w.w = pk2(v1[2], v1[3]);
;                     *(u32x4*)(XB + off) = w;
;                 }
;                 ss += __shfl_xor(ss, 16); ss += __shfl_xor(ss, 32);
;                 if (fq == 0) ssq[(size_t)row * 16 + u.pn * 4 + wc] = ss;
;                 asm volatile("" ::: "memory");
;             }
.LBB0_1031:
	s_or_b64 exec, exec, s[12:13]
	v_add_u32_e32 v34, 0xa0, v142
	s_waitcnt lgkmcnt(0)
	v_ashrrev_i32_e32 v35, 31, v34
	v_lshlrev_b64 v[36:37], 10, v[34:35]
	v_lshl_add_u64 v[36:37], v[36:37], 0, v[140:141]
	v_lshl_add_u64 v[36:37], v[36:37], 1, s[86:87]
	s_waitcnt vmcnt(18)
	s_nop 1
	v_mov_b32_e32 v38, v178
	v_mov_b32_e32 v39, v179
	v_mov_b32_e32 v40, v180
	v_mov_b32_e32 v41, v181
	v_lshlrev_b32_e32 v42, 16, v38
	v_and_b32_e32 v43, 0xffff0000, v38
	v_lshlrev_b32_e32 v38, 16, v39
	v_and_b32_e32 v39, 0xffff0000, v39
	v_lshlrev_b32_e32 v44, 16, v40
	v_and_b32_e32 v45, 0xffff0000, v40
	v_lshlrev_b32_e32 v40, 16, v41
	v_and_b32_e32 v41, 0xffff0000, v41
	v_pk_add_f32 v[32:33], v[32:33], v[38:39]
	v_pk_add_f32 v[30:31], v[30:31], v[42:43]
	v_pk_add_f32 v[38:39], v[28:29], v[40:41]
	v_pk_add_f32 v[28:29], v[26:27], v[44:45]
	v_mul_f32_e32 v26, v31, v31
	v_mul_f32_e32 v27, v33, v33
	v_fmac_f32_e32 v26, v30, v30
	v_fmac_f32_e32 v27, v32, v32
	v_add_f32_e32 v26, v26, v27
	v_mul_f32_e32 v27, v29, v29
	v_mul_f32_e32 v40, v39, v39
	v_fmac_f32_e32 v27, v28, v28
	v_fmac_f32_e32 v40, v38, v38
	v_add_f32_e32 v27, v27, v40
	v_add_f32_e32 v40, v26, v27
	v_cvt_pk_bf16_f32 v26, v30, v31
	v_cvt_pk_bf16_f32 v27, v32, v33
	v_cvt_pk_bf16_f32 v28, v28, v29
	v_cvt_pk_bf16_f32 v29, v38, v39
	global_store_dwordx4 v[36:37], v[26:29], off
	s_waitcnt vmcnt(18)
	s_nop 1
	v_mov_b32_e32 v26, v182
	v_mov_b32_e32 v27, v183
	v_mov_b32_e32 v28, v184
	v_mov_b32_e32 v29, v185
	v_lshlrev_b32_e32 v30, 16, v26
	v_and_b32_e32 v31, 0xffff0000, v26
	v_lshlrev_b32_e32 v26, 16, v27
	v_and_b32_e32 v27, 0xffff0000, v27
	v_lshlrev_b32_e32 v32, 16, v28
	v_and_b32_e32 v33, 0xffff0000, v28
	v_lshlrev_b32_e32 v28, 16, v29
	v_and_b32_e32 v29, 0xffff0000, v29
	v_pk_add_f32 v[24:25], v[24:25], v[26:27]
	v_pk_add_f32 v[22:23], v[22:23], v[30:31]
	v_pk_add_f32 v[26:27], v[20:21], v[28:29]
	v_pk_add_f32 v[20:21], v[18:19], v[32:33]
	v_mul_f32_e32 v18, v23, v23
	v_mul_f32_e32 v19, v25, v25
	v_fmac_f32_e32 v18, v22, v22
	v_fmac_f32_e32 v19, v24, v24
	v_add_f32_e32 v18, v18, v19
	v_mul_f32_e32 v19, v21, v21
	v_mul_f32_e32 v28, v27, v27
	v_fmac_f32_e32 v19, v20, v20
	v_fmac_f32_e32 v28, v26, v26
	v_add_f32_e32 v19, v19, v28
	v_add_f32_e32 v18, v18, v19
	v_add_f32_e32 v28, v40, v18
	v_cvt_pk_bf16_f32 v18, v22, v23
	v_cvt_pk_bf16_f32 v19, v24, v25
	v_cvt_pk_bf16_f32 v20, v20, v21
	v_cvt_pk_bf16_f32 v21, v26, v27
	global_store_dwordx4 v[36:37], v[18:21], off offset:256
	ds_bpermute_b32 v18, v151, v28
	s_waitcnt lgkmcnt(0)
	v_add_f32_e32 v18, v28, v18
	ds_bpermute_b32 v19, v150, v18
	s_and_saveexec_b64 s[12:13], s[42:43]
	v_lshlrev_b64 v[20:21], 6, v[34:35]
	v_lshl_add_u64 v[20:21], s[88:89], 0, v[20:21]
	v_lshl_add_u64 v[20:21], s[38:39], 2, v[20:21]
	s_lshl_b32 s8, s60, 2
	v_lshl_add_u64 v[20:21], v[20:21], 0, s[8:9]
	s_waitcnt lgkmcnt(0)
	v_add_f32_e32 v18, v18, v19
	global_store_dword v[20:21], v18, off
.LBB0_1033:
	s_or_b64 exec, exec, s[12:13]
	v_add_u32_e32 v18, 0xb0, v142
	s_waitcnt lgkmcnt(0)
	v_ashrrev_i32_e32 v19, 31, v18
	v_lshlrev_b64 v[20:21], 10, v[18:19]
	v_lshl_add_u64 v[20:21], v[20:21], 0, v[140:141]
	v_lshl_add_u64 v[20:21], v[20:21], 1, s[86:87]
	s_waitcnt vmcnt(16)
	s_nop 1
	v_mov_b32_e32 v22, v186
	v_mov_b32_e32 v23, v187
	v_mov_b32_e32 v24, v188
	v_mov_b32_e32 v25, v189
	v_lshlrev_b32_e32 v26, 16, v22
	v_and_b32_e32 v27, 0xffff0000, v22
	v_lshlrev_b32_e32 v22, 16, v23
	v_and_b32_e32 v23, 0xffff0000, v23
	v_lshlrev_b32_e32 v28, 16, v24
	v_and_b32_e32 v29, 0xffff0000, v24
	v_lshlrev_b32_e32 v24, 16, v25
	v_and_b32_e32 v25, 0xffff0000, v25
	v_pk_add_f32 v[16:17], v[16:17], v[22:23]
	v_pk_add_f32 v[14:15], v[14:15], v[26:27]
	v_pk_add_f32 v[22:23], v[12:13], v[24:25]
	v_pk_add_f32 v[12:13], v[10:11], v[28:29]
	v_mul_f32_e32 v10, v15, v15
	v_mul_f32_e32 v11, v17, v17
	v_fmac_f32_e32 v10, v14, v14
	v_fmac_f32_e32 v11, v16, v16
	v_add_f32_e32 v10, v10, v11
	v_mul_f32_e32 v11, v13, v13
	v_mul_f32_e32 v24, v23, v23
	v_fmac_f32_e32 v11, v12, v12
	v_fmac_f32_e32 v24, v22, v22
	v_add_f32_e32 v11, v11, v24
	v_add_f32_e32 v24, v10, v11
	v_cvt_pk_bf16_f32 v10, v14, v15
	v_cvt_pk_bf16_f32 v11, v16, v17
	v_cvt_pk_bf16_f32 v12, v12, v13
	v_cvt_pk_bf16_f32 v13, v22, v23
	global_store_dwordx4 v[20:21], v[10:13], off
	s_waitcnt vmcnt(16)
	s_nop 1
	v_mov_b32_e32 v10, v202
	v_mov_b32_e32 v11, v203
	v_mov_b32_e32 v12, v204
	v_mov_b32_e32 v13, v205
	v_lshlrev_b32_e32 v14, 16, v10
	v_and_b32_e32 v15, 0xffff0000, v10
	v_lshlrev_b32_e32 v10, 16, v11
	v_and_b32_e32 v11, 0xffff0000, v11
	v_lshlrev_b32_e32 v16, 16, v12
	v_and_b32_e32 v17, 0xffff0000, v12
	v_lshlrev_b32_e32 v12, 16, v13
	v_and_b32_e32 v13, 0xffff0000, v13
	v_pk_add_f32 v[8:9], v[8:9], v[10:11]
	v_pk_add_f32 v[6:7], v[6:7], v[14:15]
	v_pk_add_f32 v[10:11], v[4:5], v[12:13]
	v_pk_add_f32 v[4:5], v[2:3], v[16:17]
	v_mul_f32_e32 v2, v7, v7
	v_mul_f32_e32 v3, v9, v9
	v_fmac_f32_e32 v2, v6, v6
	v_fmac_f32_e32 v3, v8, v8
	v_add_f32_e32 v2, v2, v3
	v_mul_f32_e32 v3, v5, v5
	v_mul_f32_e32 v12, v11, v11
	v_fmac_f32_e32 v3, v4, v4
	v_fmac_f32_e32 v12, v10, v10
	v_add_f32_e32 v3, v3, v12
	v_add_f32_e32 v2, v2, v3
	v_add_f32_e32 v12, v24, v2
	v_cvt_pk_bf16_f32 v2, v6, v7
	v_cvt_pk_bf16_f32 v3, v8, v9
	v_cvt_pk_bf16_f32 v4, v4, v5
	v_cvt_pk_bf16_f32 v5, v10, v11
	global_store_dwordx4 v[20:21], v[2:5], off offset:256
	ds_bpermute_b32 v2, v151, v12
	s_waitcnt lgkmcnt(0)
	v_add_f32_e32 v2, v12, v2
	ds_bpermute_b32 v3, v150, v2
	s_and_saveexec_b64 s[12:13], s[42:43]
	v_lshlrev_b64 v[4:5], 6, v[18:19]
	v_lshl_add_u64 v[4:5], s[88:89], 0, v[4:5]
	v_lshl_add_u64 v[4:5], s[38:39], 2, v[4:5]
	s_lshl_b32 s8, s60, 2
	v_lshl_add_u64 v[4:5], v[4:5], 0, s[8:9]
	s_waitcnt lgkmcnt(0)
	v_add_f32_e32 v2, v2, v3
	global_store_dword v[4:5], v2, off

; #define PG8_STAGE(bufoff, gbase, voff) do { _Pragma("unroll") for (int _i = 0; _i < 2; ++_i) \
;         __builtin_amdgcn_global_load_lds((const unsigned*)((const char*)(gbase) + (voff)[_i]), (PG8_LAS unsigned*)(lds + (bufoff) + ldsw + _i * 8192), 16, 0, 0); } while (0)
; #define PG8_LDA(dst, b, h) do { _Pragma("unroll") for (int m = 0; m < 4; ++m) _Pragma("unroll") for (int k = 0; k < 2; ++k) dst[m][k] = *(const PG8_LAS bf16x8*)(lds + PG8_SA(b, h) + aoff + m * 2048 + k * 1024); } while (0)
; #define PG8_LDB(dst, b, h) do { _Pragma("unroll") for (int n = 0; n < 2; ++n) _Pragma("unroll") for (int k = 0; k < 2; ++k) dst[n][k] = *(const PG8_LAS bf16x8*)(lds + PG8_SB(b, h) + boff + n * 2048 + k * 1024); } while (0)
; #define PG8_MMA_NP(ai, bj, At, Bt) do { _Pragma("unroll") for (int m = 0; m < 4; ++m) _Pragma("unroll") for (int n = 0; n < 2; ++n) _Pragma("unroll") for (int k = 0; k < 2; ++k) \
;         acc[ai][bj][m][n] = __builtin_amdgcn_mfma_f32_16x16x32_bf16(Bt[n][k], At[m][k], acc[ai][bj][m][n], 0, 0, 0); } while (0)
; #define PG8_BAR __builtin_amdgcn_s_barrier()
; template <class Epi, class Sched, bool ALIGN_EPI = false, bool SP2 = false>
; __device__ __forceinline__ void gemm_phase(PG8_LAS unsigned char* lds, const Gemm g, const Sched& S, const Epi& E) {
;     ...
;         for (int t = 0; t < nt; t += 2) {
;             const bool last = (t == nt - 2);
;             const char* a1 = cA + (size_t)(t + 1) * kstep;
;             const char* a2 = last ? nA : cA + (size_t)(t + 2) * kstep; const char* b2 = last ? nB : cB + (size_t)(t + 2) * kstep;
;             const char* a3 = a2 + kstep; const char* b3 = b2 + kstep;
;             if (last && has_next) S.a_ready(nxt);
;             if constexpr (SP2) {
;             PG8_LDB(B0, 0, 0); PG8_LDB(B1, 0, 1); PG8_SCHED; PG8_LDA(At, 0, 0); PG8_STAGE(PG8_SA(1, 1), a1 + hstep, voffA);
;             PG8_WAIT_V(8); PG8_WAIT_L(0); PG8_BAR; __builtin_amdgcn_s_setprio(1); PG8_MMA_NP(0, 0, At, B0); PG8_MMA_NP(0, 1, At, B1); __builtin_amdgcn_s_setprio(0); PG8_BAR; PG8_SCHED;
;             PG8_LDA(At, 0, 1); PG8_STAGE(PG8_SB(0, 0), b2, voffB); PG8_STAGE(PG8_SB(0, 1), b2 + hstep, voffB); PG8_STAGE(PG8_SA(0, 0), a2, voffA);
;             PG8_WAIT_V(8); PG8_WAIT_L(0); PG8_BAR; __builtin_amdgcn_s_setprio(1); PG8_MMA_NP(1, 0, At, B0); PG8_MMA_NP(1, 1, At, B1); __builtin_amdgcn_s_setprio(0); PG8_BAR; PG8_SCHED;
.LBB0_1220:
	s_add_u32 s48, s12, 0x100
	s_addc_u32 s49, s13, 0
	s_add_i32 s22, 0, 0x10000
	s_cmp_eq_u32 s64, 40
	s_cselect_b32 s51, s43, s49
	s_cselect_b32 s50, s42, s48
	v_add_u32_e32 v144, s22, v147
	s_cselect_b32 s15, s47, s63
	s_cselect_b32 s14, s46, s62
	s_add_i32 s23, 0, 0x14000
	ds_read_b128 v[140:143], v144
	ds_read_b128 v[150:153], v144 offset:1024
	ds_read_b128 v[154:157], v144 offset:2048
	ds_read_b128 v[158:161], v144 offset:3072
	v_add_u32_e32 v144, s23, v147
	ds_read_b128 v[178:181], v144
	ds_read_b128 v[182:185], v144 offset:1024
	ds_read_b128 v[186:189], v144 offset:2048
	ds_read_b128 v[202:205], v144 offset:3072
	v_lshl_add_u64 v[144:145], s[12:13], 0, v[136:137]
	s_add_i32 m0, s52, 0xc000
	ds_read_b128 v[206:209], v149
	ds_read_b128 v[210:213], v149 offset:1024
	ds_read_b128 v[214:217], v149 offset:2048
	ds_read_b128 v[218:221], v149 offset:3072
	ds_read_b128 v[222:225], v149 offset:4096
	ds_read_b128 v[226:229], v149 offset:5120
	ds_read_b128 v[230:233], v149 offset:6144
	ds_read_b128 v[234:237], v149 offset:7168
	global_load_lds_dwordx4 v[144:145], off
	v_lshl_add_u64 v[144:145], s[12:13], 0, v[138:139]
	s_add_i32 m0, s52, 0xe000
	s_nop 0
	global_load_lds_dwordx4 v[144:145], off
	s_waitcnt vmcnt(8)
	s_waitcnt lgkmcnt(0)
	s_barrier
	s_setprio 1
	s_waitcnt lgkmcnt(0)
	v_mfma_f32_16x16x32_bf16 v[126:129], v[140:143], v[206:209], v[126:129]
	v_mfma_f32_16x16x32_bf16 v[122:125], v[154:157], v[206:209], v[122:125]
	v_mfma_f32_16x16x32_bf16 v[110:113], v[140:143], v[214:217], v[110:113]
	v_mfma_f32_16x16x32_bf16 v[106:109], v[154:157], v[214:217], v[106:109]
	v_mfma_f32_16x16x32_bf16 v[94:97], v[140:143], v[222:225], v[94:97]
	v_mfma_f32_16x16x32_bf16 v[90:93], v[154:157], v[222:225], v[90:93]
	v_mfma_f32_16x16x32_bf16 v[78:81], v[140:143], v[230:233], v[78:81]
	v_mfma_f32_16x16x32_bf16 v[74:77], v[154:157], v[230:233], v[74:77]
	v_mfma_f32_16x16x32_bf16 v[118:121], v[178:181], v[206:209], v[118:121]
	v_mfma_f32_16x16x32_bf16 v[114:117], v[186:189], v[206:209], v[114:117]
	v_mfma_f32_16x16x32_bf16 v[102:105], v[178:181], v[214:217], v[102:105]
	v_mfma_f32_16x16x32_bf16 v[98:101], v[186:189], v[214:217], v[98:101]
	v_mfma_f32_16x16x32_bf16 v[86:89], v[178:181], v[222:225], v[86:89]
	v_mfma_f32_16x16x32_bf16 v[82:85], v[186:189], v[222:225], v[82:85]
	v_mfma_f32_16x16x32_bf16 v[70:73], v[178:181], v[230:233], v[70:73]
	v_mfma_f32_16x16x32_bf16 v[66:69], v[186:189], v[230:233], v[66:69]
	v_mfma_f32_16x16x32_bf16 v[126:129], v[150:153], v[210:213], v[126:129]
	v_mfma_f32_16x16x32_bf16 v[122:125], v[158:161], v[210:213], v[122:125]
	v_mfma_f32_16x16x32_bf16 v[110:113], v[150:153], v[218:221], v[110:113]
	v_mfma_f32_16x16x32_bf16 v[106:109], v[158:161], v[218:221], v[106:109]
	v_mfma_f32_16x16x32_bf16 v[94:97], v[150:153], v[226:229], v[94:97]
	v_mfma_f32_16x16x32_bf16 v[90:93], v[158:161], v[226:229], v[90:93]
	v_mfma_f32_16x16x32_bf16 v[78:81], v[150:153], v[234:237], v[78:81]
	v_mfma_f32_16x16x32_bf16 v[74:77], v[158:161], v[234:237], v[74:77]
	v_mfma_f32_16x16x32_bf16 v[118:121], v[182:185], v[210:213], v[118:121]
	v_mfma_f32_16x16x32_bf16 v[114:117], v[202:205], v[210:213], v[114:117]
	v_mfma_f32_16x16x32_bf16 v[102:105], v[182:185], v[218:221], v[102:105]
	v_mfma_f32_16x16x32_bf16 v[98:101], v[202:205], v[218:221], v[98:101]
	v_mfma_f32_16x16x32_bf16 v[86:89], v[182:185], v[226:229], v[86:89]
	v_mfma_f32_16x16x32_bf16 v[82:85], v[202:205], v[226:229], v[82:85]
	v_mfma_f32_16x16x32_bf16 v[70:73], v[182:185], v[234:237], v[70:73]
	v_mfma_f32_16x16x32_bf16 v[66:69], v[202:205], v[234:237], v[66:69]
	s_setprio 0
	s_barrier
	s_add_i32 s12, s22, s31
	v_lshl_add_u64 v[144:145], s[14:15], 0, v[0:1]
	s_mov_b32 m0, s12
	ds_read_b128 v[206:209], v149 offset:16384
	ds_read_b128 v[210:213], v149 offset:17408
	ds_read_b128 v[214:217], v149 offset:18432
	ds_read_b128 v[218:221], v149 offset:19456
	ds_read_b128 v[222:225], v149 offset:20480
	ds_read_b128 v[226:229], v149 offset:21504
	ds_read_b128 v[230:233], v149 offset:22528
	ds_read_b128 v[234:237], v149 offset:23552
	global_load_lds_dwordx4 v[144:145], off
	s_add_i32 m0, s12, 0x2000
	s_add_u32 s12, s14, 0xb0000
	v_lshl_add_u64 v[162:163], s[14:15], 0, v[130:131]
	s_addc_u32 s13, s15, 0
	s_add_i32 s22, s23, s31
	global_load_lds_dwordx4 v[162:163], off
	v_lshl_add_u64 v[190:191], s[12:13], 0, v[0:1]
	s_mov_b32 m0, s22
	v_lshl_add_u64 v[238:239], s[50:51], 0, v[132:133]
	global_load_lds_dwordx4 v[190:191], off
	v_lshl_add_u64 v[190:191], s[12:13], 0, v[130:131]
	s_add_i32 m0, s22, 0x2000
	s_nop 0
	global_load_lds_dwordx4 v[190:191], off
	v_lshl_add_u64 v[190:191], s[50:51], 0, v[134:135]
	s_mov_b32 m0, s52
	s_nop 0
	global_load_lds_dwordx4 v[190:191], off
	s_mov_b32 m0, s53
	s_nop 0
	global_load_lds_dwordx4 v[238:239], off
	s_waitcnt vmcnt(8)
	s_waitcnt lgkmcnt(0)
	s_barrier
; #define PG8_STAGE(bufoff, gbase, voff) do { _Pragma("unroll") for (int _i = 0; _i < 2; ++_i) \
;         __builtin_amdgcn_global_load_lds((const unsigned*)((const char*)(gbase) + (voff)[_i]), (PG8_LAS unsigned*)(lds + (bufoff) + ldsw + _i * 8192), 16, 0, 0); } while (0)
; #define PG8_LDA(dst, b, h) do { _Pragma("unroll") for (int m = 0; m < 4; ++m) _Pragma("unroll") for (int k = 0; k < 2; ++k) dst[m][k] = *(const PG8_LAS bf16x8*)(lds + PG8_SA(b, h) + aoff + m * 2048 + k * 1024); } while (0)
; #define PG8_LDB(dst, b, h) do { _Pragma("unroll") for (int n = 0; n < 2; ++n) _Pragma("unroll") for (int k = 0; k < 2; ++k) dst[n][k] = *(const PG8_LAS bf16x8*)(lds + PG8_SB(b, h) + boff + n * 2048 + k * 1024); } while (0)
; #define PG8_MMA_NP(ai, bj, At, Bt) do { _Pragma("unroll") for (int m = 0; m < 4; ++m) _Pragma("unroll") for (int n = 0; n < 2; ++n) _Pragma("unroll") for (int k = 0; k < 2; ++k) \
;         acc[ai][bj][m][n] = __builtin_amdgcn_mfma_f32_16x16x32_bf16(Bt[n][k], At[m][k], acc[ai][bj][m][n], 0, 0, 0); } while (0)
; #define PG8_WAIT_V(n) asm volatile("s_waitcnt vmcnt(" #n ")" ::: "memory")
; #define PG8_WAIT_L(n) asm volatile("s_waitcnt lgkmcnt(" #n ")" ::: "memory")
; #define PG8_BAR __builtin_amdgcn_s_barrier()
; #define PG8_SCHED __builtin_amdgcn_sched_barrier(0)
; template <class Epi, class Sched, bool ALIGN_EPI = false, bool SP2 = false>
; __device__ __forceinline__ void gemm_phase(PG8_LAS unsigned char* lds, const Gemm g, const Sched& S, const Epi& E) {
;     ...
;             PG8_WAIT_V(8); PG8_WAIT_L(0); PG8_BAR; __builtin_amdgcn_s_setprio(1); PG8_MMA_NP(1, 0, At, B0); PG8_MMA_NP(1, 1, At, B1); __builtin_amdgcn_s_setprio(0); PG8_BAR; PG8_SCHED;
;             PG8_LDB(B0, 1, 0); PG8_LDB(B1, 1, 1); PG8_SCHED; PG8_LDA(At, 1, 0); PG8_STAGE(PG8_SA(0, 1), a2 + hstep, voffA);
;             PG8_WAIT_V(8); PG8_WAIT_L(0); PG8_BAR; __builtin_amdgcn_s_setprio(1); PG8_MMA_NP(0, 0, At, B0); PG8_MMA_NP(0, 1, At, B1); __builtin_amdgcn_s_setprio(0); PG8_BAR; PG8_SCHED;
	s_setprio 1
	s_waitcnt lgkmcnt(0)
	v_mfma_f32_16x16x32_bf16 v[62:65], v[140:143], v[206:209], v[62:65]
	v_mfma_f32_16x16x32_bf16 v[58:61], v[154:157], v[206:209], v[58:61]
	v_mfma_f32_16x16x32_bf16 v[46:49], v[140:143], v[214:217], v[46:49]
	v_mfma_f32_16x16x32_bf16 v[42:45], v[154:157], v[214:217], v[42:45]
	v_mfma_f32_16x16x32_bf16 v[30:33], v[140:143], v[222:225], v[30:33]
	v_mfma_f32_16x16x32_bf16 v[26:29], v[154:157], v[222:225], v[26:29]
	v_mfma_f32_16x16x32_bf16 v[14:17], v[140:143], v[230:233], v[14:17]
	v_mfma_f32_16x16x32_bf16 v[10:13], v[154:157], v[230:233], v[10:13]
	v_mfma_f32_16x16x32_bf16 v[54:57], v[178:181], v[206:209], v[54:57]
	v_mfma_f32_16x16x32_bf16 v[50:53], v[186:189], v[206:209], v[50:53]
	v_mfma_f32_16x16x32_bf16 v[38:41], v[178:181], v[214:217], v[38:41]
	v_mfma_f32_16x16x32_bf16 v[34:37], v[186:189], v[214:217], v[34:37]
	v_mfma_f32_16x16x32_bf16 v[22:25], v[178:181], v[222:225], v[22:25]
	v_mfma_f32_16x16x32_bf16 v[18:21], v[186:189], v[222:225], v[18:21]
	v_mfma_f32_16x16x32_bf16 v[6:9], v[178:181], v[230:233], v[6:9]
	v_mfma_f32_16x16x32_bf16 v[2:5], v[186:189], v[230:233], v[2:5]
	v_mfma_f32_16x16x32_bf16 v[62:65], v[150:153], v[210:213], v[62:65]
	v_mfma_f32_16x16x32_bf16 v[58:61], v[158:161], v[210:213], v[58:61]
	v_mfma_f32_16x16x32_bf16 v[46:49], v[150:153], v[218:221], v[46:49]
	v_mfma_f32_16x16x32_bf16 v[42:45], v[158:161], v[218:221], v[42:45]
	v_mfma_f32_16x16x32_bf16 v[30:33], v[150:153], v[226:229], v[30:33]
	v_mfma_f32_16x16x32_bf16 v[26:29], v[158:161], v[226:229], v[26:29]
	v_mfma_f32_16x16x32_bf16 v[14:17], v[150:153], v[234:237], v[14:17]
	v_mfma_f32_16x16x32_bf16 v[10:13], v[158:161], v[234:237], v[10:13]
	v_mfma_f32_16x16x32_bf16 v[54:57], v[182:185], v[210:213], v[54:57]
	v_mfma_f32_16x16x32_bf16 v[50:53], v[202:205], v[210:213], v[50:53]
	v_mfma_f32_16x16x32_bf16 v[38:41], v[182:185], v[218:221], v[38:41]
	v_mfma_f32_16x16x32_bf16 v[34:37], v[202:205], v[218:221], v[34:37]
	v_mfma_f32_16x16x32_bf16 v[22:25], v[182:185], v[226:229], v[22:25]
	v_mfma_f32_16x16x32_bf16 v[18:21], v[202:205], v[226:229], v[18:21]
	v_mfma_f32_16x16x32_bf16 v[6:9], v[182:185], v[234:237], v[6:9]
	v_mfma_f32_16x16x32_bf16 v[2:5], v[202:205], v[234:237], v[2:5]
	s_setprio 0
	s_barrier
	s_add_i32 s22, 0, 0x18000
	s_add_i32 s23, 0, 0x1c000
	v_add_u32_e32 v158, s22, v147
	v_add_u32_e32 v202, s23, v147
	ds_read_b128 v[140:143], v158
	ds_read_b128 v[150:153], v158 offset:1024
	ds_read_b128 v[154:157], v158 offset:2048
	ds_read_b128 v[158:161], v158 offset:3072
	ds_read_b128 v[178:181], v202
	ds_read_b128 v[182:185], v202 offset:1024
	ds_read_b128 v[186:189], v202 offset:2048
	ds_read_b128 v[202:205], v202 offset:3072
	s_add_u32 s12, s50, 0xb0000
	s_addc_u32 s13, s51, 0
	s_mov_b32 m0, s54
	v_lshl_add_u64 v[240:241], s[12:13], 0, v[134:135]
	ds_read_b128 v[206:209], v149 offset:32768
	ds_read_b128 v[210:213], v149 offset:33792
	ds_read_b128 v[214:217], v149 offset:34816
	ds_read_b128 v[218:221], v149 offset:35840
	ds_read_b128 v[222:225], v149 offset:36864
	ds_read_b128 v[226:229], v149 offset:37888
	ds_read_b128 v[230:233], v149 offset:38912
	ds_read_b128 v[234:237], v149 offset:39936
	global_load_lds_dwordx4 v[240:241], off
	v_lshl_add_u64 v[240:241], s[12:13], 0, v[132:133]
	s_mov_b32 m0, s55
	s_nop 0
	global_load_lds_dwordx4 v[240:241], off
	s_waitcnt vmcnt(8)
	s_waitcnt lgkmcnt(0)
	s_barrier
	s_setprio 1
	s_waitcnt lgkmcnt(0)
	v_mfma_f32_16x16x32_bf16 v[126:129], v[140:143], v[206:209], v[126:129]
	v_mfma_f32_16x16x32_bf16 v[122:125], v[154:157], v[206:209], v[122:125]
	v_mfma_f32_16x16x32_bf16 v[110:113], v[140:143], v[214:217], v[110:113]
	v_mfma_f32_16x16x32_bf16 v[106:109], v[154:157], v[214:217], v[106:109]
	v_mfma_f32_16x16x32_bf16 v[94:97], v[140:143], v[222:225], v[94:97]
	v_mfma_f32_16x16x32_bf16 v[90:93], v[154:157], v[222:225], v[90:93]
	v_mfma_f32_16x16x32_bf16 v[78:81], v[140:143], v[230:233], v[78:81]
	v_mfma_f32_16x16x32_bf16 v[74:77], v[154:157], v[230:233], v[74:77]
	v_mfma_f32_16x16x32_bf16 v[118:121], v[178:181], v[206:209], v[118:121]
	v_mfma_f32_16x16x32_bf16 v[114:117], v[186:189], v[206:209], v[114:117]
	v_mfma_f32_16x16x32_bf16 v[102:105], v[178:181], v[214:217], v[102:105]
	v_mfma_f32_16x16x32_bf16 v[98:101], v[186:189], v[214:217], v[98:101]
	v_mfma_f32_16x16x32_bf16 v[86:89], v[178:181], v[222:225], v[86:89]
	v_mfma_f32_16x16x32_bf16 v[82:85], v[186:189], v[222:225], v[82:85]
	v_mfma_f32_16x16x32_bf16 v[70:73], v[178:181], v[230:233], v[70:73]
	v_mfma_f32_16x16x32_bf16 v[66:69], v[186:189], v[230:233], v[66:69]
	v_mfma_f32_16x16x32_bf16 v[126:129], v[150:153], v[210:213], v[126:129]
	v_mfma_f32_16x16x32_bf16 v[122:125], v[158:161], v[210:213], v[122:125]
	v_mfma_f32_16x16x32_bf16 v[110:113], v[150:153], v[218:221], v[110:113]
	v_mfma_f32_16x16x32_bf16 v[106:109], v[158:161], v[218:221], v[106:109]
	v_mfma_f32_16x16x32_bf16 v[94:97], v[150:153], v[226:229], v[94:97]
	v_mfma_f32_16x16x32_bf16 v[90:93], v[158:161], v[226:229], v[90:93]
	v_mfma_f32_16x16x32_bf16 v[78:81], v[150:153], v[234:237], v[78:81]
	v_mfma_f32_16x16x32_bf16 v[74:77], v[158:161], v[234:237], v[74:77]
	v_mfma_f32_16x16x32_bf16 v[118:121], v[182:185], v[210:213], v[118:121]
	v_mfma_f32_16x16x32_bf16 v[114:117], v[202:205], v[210:213], v[114:117]
	v_mfma_f32_16x16x32_bf16 v[102:105], v[182:185], v[218:221], v[102:105]
	v_mfma_f32_16x16x32_bf16 v[98:101], v[202:205], v[218:221], v[98:101]
	v_mfma_f32_16x16x32_bf16 v[86:89], v[182:185], v[226:229], v[86:89]
	v_mfma_f32_16x16x32_bf16 v[82:85], v[202:205], v[226:229], v[82:85]
	v_mfma_f32_16x16x32_bf16 v[70:73], v[182:185], v[234:237], v[70:73]
	v_mfma_f32_16x16x32_bf16 v[66:69], v[202:205], v[234:237], v[66:69]
	s_setprio 0
	s_barrier
; #define PG8_STAGE(bufoff, gbase, voff) do { _Pragma("unroll") for (int _i = 0; _i < 2; ++_i) \
;         __builtin_amdgcn_global_load_lds((const unsigned*)((const char*)(gbase) + (voff)[_i]), (PG8_LAS unsigned*)(lds + (bufoff) + ldsw + _i * 8192), 16, 0, 0); } while (0)
; #define PG8_LDA(dst, b, h) do { _Pragma("unroll") for (int m = 0; m < 4; ++m) _Pragma("unroll") for (int k = 0; k < 2; ++k) dst[m][k] = *(const PG8_LAS bf16x8*)(lds + PG8_SA(b, h) + aoff + m * 2048 + k * 1024); } while (0)
; #define PG8_MMA_NP(ai, bj, At, Bt) do { _Pragma("unroll") for (int m = 0; m < 4; ++m) _Pragma("unroll") for (int n = 0; n < 2; ++n) _Pragma("unroll") for (int k = 0; k < 2; ++k) \
;         acc[ai][bj][m][n] = __builtin_amdgcn_mfma_f32_16x16x32_bf16(Bt[n][k], At[m][k], acc[ai][bj][m][n], 0, 0, 0); } while (0)
; #define PG8_WAIT_V(n) asm volatile("s_waitcnt vmcnt(" #n ")" ::: "memory")
; #define PG8_WAIT_L(n) asm volatile("s_waitcnt lgkmcnt(" #n ")" ::: "memory")
; #define PG8_BAR __builtin_amdgcn_s_barrier()
; #define PG8_SCHED __builtin_amdgcn_sched_barrier(0)
; DI float bflo(unsigned w) { return __uint_as_float(w << 16); }
; template <class Epi, class Sched, bool ALIGN_EPI = false, bool SP2 = false>
; __device__ __forceinline__ void gemm_phase(PG8_LAS unsigned char* lds, const Gemm g, const Sched& S, const Epi& E) {
;     ...
;             PG8_LDA(At, 1, 1); PG8_STAGE(PG8_SB(1, 0), b3, voffB); PG8_STAGE(PG8_SB(1, 1), b3 + hstep, voffB); PG8_STAGE(PG8_SA(1, 0), a3, voffA);
;             PG8_WAIT_V(8); PG8_WAIT_L(0); PG8_BAR; __builtin_amdgcn_s_setprio(1); PG8_MMA_NP(1, 0, At, B0); PG8_MMA_NP(1, 1, At, B1); __builtin_amdgcn_s_setprio(0); PG8_BAR; PG8_SCHED;
;     DI void operator()(const f32x4 (&acc)[2][2][4][2], const pg8::Unit& u, int wr, int wc, int fr, int fq) const {
;     ...
;                 const int row = row0 + ai * 128 + m * 16; float ss = 0.f;
; #pragma unroll
;                 for (int bj = 0; bj < 2; ++bj) {
;                     const size_t off = (size_t)row * DM + col0 + bj * 128;
;                     f32x4 b0, b1;
;                     if (base32) { b0 = *(const f32x4*)(base32 + off); b1 = *(const f32x4*)(base32 + off + 4); }
;                     else { const u32x4 bb = *(const u32x4*)(XB + off); b0 = (f32x4){bflo(bb.x), bfhi(bb.x), bflo(bb.y), bfhi(bb.y)}; b1 = (f32x4){bflo(bb.z), bfhi(bb.z), bflo(bb.w), bfhi(bb.w)}; }
	s_add_i32 s12, s22, s31
	v_lshl_add_u64 v[144:145], v[144:145], 0, s[20:21]
	s_mov_b32 m0, s12
	ds_read_b128 v[206:209], v149 offset:49152
	ds_read_b128 v[210:213], v149 offset:50176
	ds_read_b128 v[214:217], v149 offset:51200
	ds_read_b128 v[218:221], v149 offset:52224
	ds_read_b128 v[222:225], v149 offset:53248
	ds_read_b128 v[226:229], v149 offset:54272
	ds_read_b128 v[230:233], v149 offset:55296
	ds_read_b128 v[234:237], v149 offset:56320
	global_load_lds_dwordx4 v[144:145], off
	s_add_i32 m0, s12, 0x2000
	s_add_u32 s12, s14, 0xb0080
	v_lshl_add_u64 v[144:145], v[162:163], 0, s[20:21]
	s_addc_u32 s13, s15, 0
	s_add_i32 s14, s23, s31
	global_load_lds_dwordx4 v[144:145], off
	v_lshl_add_u64 v[144:145], s[12:13], 0, v[0:1]
	s_mov_b32 m0, s14
	s_nop 0
	global_load_lds_dwordx4 v[144:145], off
	v_lshl_add_u64 v[144:145], s[12:13], 0, v[130:131]
	s_add_i32 m0, s14, 0x2000
	s_nop 0
	global_load_lds_dwordx4 v[144:145], off
	v_lshl_add_u64 v[144:145], v[190:191], 0, s[20:21]
	s_mov_b32 m0, s57
	s_nop 0
	global_load_lds_dwordx4 v[144:145], off
	v_lshl_add_u64 v[144:145], v[238:239], 0, s[20:21]
	s_mov_b32 m0, s58
	s_nop 0
	global_load_lds_dwordx4 v[144:145], off
	s_waitcnt vmcnt(8)
	s_waitcnt lgkmcnt(0)
	s_barrier
	s_setprio 1
	s_waitcnt lgkmcnt(0)
	v_mfma_f32_16x16x32_bf16 v[62:65], v[140:143], v[206:209], v[62:65]
	v_mfma_f32_16x16x32_bf16 v[58:61], v[154:157], v[206:209], v[58:61]
	v_mfma_f32_16x16x32_bf16 v[46:49], v[140:143], v[214:217], v[46:49]
	v_mfma_f32_16x16x32_bf16 v[42:45], v[154:157], v[214:217], v[42:45]
	v_mfma_f32_16x16x32_bf16 v[30:33], v[140:143], v[222:225], v[30:33]
	v_mfma_f32_16x16x32_bf16 v[26:29], v[154:157], v[222:225], v[26:29]
	v_mfma_f32_16x16x32_bf16 v[14:17], v[140:143], v[230:233], v[14:17]
	v_mfma_f32_16x16x32_bf16 v[10:13], v[154:157], v[230:233], v[10:13]
	v_mfma_f32_16x16x32_bf16 v[54:57], v[178:181], v[206:209], v[54:57]
	v_mfma_f32_16x16x32_bf16 v[50:53], v[186:189], v[206:209], v[50:53]
	v_mfma_f32_16x16x32_bf16 v[38:41], v[178:181], v[214:217], v[38:41]
	v_mfma_f32_16x16x32_bf16 v[34:37], v[186:189], v[214:217], v[34:37]
	v_mfma_f32_16x16x32_bf16 v[22:25], v[178:181], v[222:225], v[22:25]
	v_mfma_f32_16x16x32_bf16 v[18:21], v[186:189], v[222:225], v[18:21]
	v_mfma_f32_16x16x32_bf16 v[6:9], v[178:181], v[230:233], v[6:9]
	v_mfma_f32_16x16x32_bf16 v[2:5], v[186:189], v[230:233], v[2:5]
	v_mfma_f32_16x16x32_bf16 v[62:65], v[150:153], v[210:213], v[62:65]
	v_mfma_f32_16x16x32_bf16 v[58:61], v[158:161], v[210:213], v[58:61]
	v_mfma_f32_16x16x32_bf16 v[46:49], v[150:153], v[218:221], v[46:49]
	v_mfma_f32_16x16x32_bf16 v[42:45], v[158:161], v[218:221], v[42:45]
	v_mfma_f32_16x16x32_bf16 v[30:33], v[150:153], v[226:229], v[30:33]
	v_mfma_f32_16x16x32_bf16 v[26:29], v[158:161], v[226:229], v[26:29]
	v_mfma_f32_16x16x32_bf16 v[14:17], v[150:153], v[234:237], v[14:17]
	v_mfma_f32_16x16x32_bf16 v[10:13], v[158:161], v[234:237], v[10:13]
	v_mfma_f32_16x16x32_bf16 v[54:57], v[182:185], v[210:213], v[54:57]
	v_mfma_f32_16x16x32_bf16 v[50:53], v[202:205], v[210:213], v[50:53]
	v_mfma_f32_16x16x32_bf16 v[38:41], v[182:185], v[218:221], v[38:41]
	v_mfma_f32_16x16x32_bf16 v[34:37], v[202:205], v[218:221], v[34:37]
	v_mfma_f32_16x16x32_bf16 v[22:25], v[182:185], v[226:229], v[22:25]
	v_mfma_f32_16x16x32_bf16 v[18:21], v[202:205], v[226:229], v[18:21]
	v_mfma_f32_16x16x32_bf16 v[6:9], v[182:185], v[234:237], v[6:9]
	v_mfma_f32_16x16x32_bf16 v[2:5], v[202:205], v[234:237], v[2:5]
	s_setprio 0
	s_barrier
	s_add_i32 s64, s64, 2
	s_add_u32 s62, s62, 0x100
	s_addc_u32 s63, s63, 0
	s_cmp_gt_u32 s64, 41
	s_mov_b64 s[12:13], s[48:49]
	s_cbranch_scc0 .LBB0_1220
	v_lshl_add_u32 v160, s61, 8, v146
	v_ashrrev_i32_e32 v161, 31, v160
	v_lshl_or_b32 v162, s8, 8, v148
	v_ashrrev_i32_e32 v163, 31, v162
	v_lshlrev_b64 v[160:161], 10, v[160:161]
	v_lshl_add_u64 v[160:161], v[160:161], 0, v[162:163]
	v_lshl_add_u64 v[160:161], v[160:161], 1, s[86:87]
	global_load_dwordx4 v[178:181], v[160:161], off
	global_load_dwordx4 v[182:185], v[160:161], off offset:256
	s_mov_b64 vcc, 0x8000
	v_lshl_add_u64 v[162:163], v[160:161], 0, vcc
	global_load_dwordx4 v[186:189], v[162:163], off
	global_load_dwordx4 v[202:205], v[162:163], off offset:256
	s_mov_b64 vcc, 0x10000
	v_lshl_add_u64 v[162:163], v[160:161], 0, vcc
	global_load_dwordx4 v[206:209], v[162:163], off
	global_load_dwordx4 v[210:213], v[162:163], off offset:256
	s_mov_b64 vcc, 0x18000
	v_lshl_add_u64 v[162:163], v[160:161], 0, vcc
	global_load_dwordx4 v[214:217], v[162:163], off
	global_load_dwordx4 v[218:221], v[162:163], off offset:256
	s_mov_b64 vcc, 0x40000
	v_lshl_add_u64 v[162:163], v[160:161], 0, vcc
	global_load_dwordx4 v[222:225], v[162:163], off
	global_load_dwordx4 v[226:229], v[162:163], off offset:256
	s_mov_b64 vcc, 0x48000
	v_lshl_add_u64 v[162:163], v[160:161], 0, vcc
	global_load_dwordx4 v[230:233], v[162:163], off
	global_load_dwordx4 v[234:237], v[162:163], off offset:256
	s_and_b64 vcc, exec, s[44:45]
	s_cbranch_vccz .LBB0_1223
	s_barrier
; DI unsigned pk2(float lo, float hi) { return pg8::cvt_pk_bf16(lo, hi); }
; DI float bflo(unsigned w) { return __uint_as_float(w << 16); }
; DI float bfhi(unsigned w) { return __uint_as_float(w & 0xffff0000u); }
;     DI void operator()(const f32x4 (&acc)[2][2][4][2], const pg8::Unit& u, int wr, int wc, int fr, int fq) const {
;         const int row0 = u.pm * 256 + wr * 64 + fr, col0 = u.pn * 256 + wc * 32 + 8 * fq;
; #pragma unroll
;         for (int ai = 0; ai < 2; ++ai)
; #pragma unroll
;             for (int m = 0; m < 4; ++m) {
;                 const int row = row0 + ai * 128 + m * 16; float ss = 0.f;
; #pragma unroll
;                 for (int bj = 0; bj < 2; ++bj) {
;                     const size_t off = (size_t)row * DM + col0 + bj * 128;
;                     f32x4 b0, b1;
;                     if (base32) { b0 = *(const f32x4*)(base32 + off); b1 = *(const f32x4*)(base32 + off + 4); }
;                     else { const u32x4 bb = *(const u32x4*)(XB + off); b0 = (f32x4){bflo(bb.x), bfhi(bb.x), bflo(bb.y), bfhi(bb.y)}; b1 = (f32x4){bflo(bb.z), bfhi(bb.z), bflo(bb.w), bfhi(bb.w)}; }
;                     const f32x4 v0 = b0 + acc[ai][bj][m][0] * alpha, v1 = b1 + acc[ai][bj][m][1] * alpha;
;                     ss += ((v0[0] * v0[0] + v0[1] * v0[1]) + (v0[2] * v0[2] + v0[3] * v0[3])) + ((v1[0] * v1[0] + v1[1] * v1[1]) + (v1[2] * v1[2] + v1[3] * v1[3]));
;                     u32x4 w; w.x = pk2(v0[0], v0[1]); w.y = pk2(v0[2], v0[3]); w.z = pk2(v1[0], v1[1]); w.w = pk2(v1[2], v1[3]);
;                     *(u32x4*)(XB + off) = w;
;                 }
;                 ss += __shfl_xor(ss, 16); ss += __shfl_xor(ss, 32);
;                 if (fq == 0) ssq[(size_t)row * 16 + u.pn * 4 + wc] = ss;
;                 asm volatile("" ::: "memory");
;             }
.LBB0_1223:
	v_and_b32_e32 v144, 64, v194
	v_xor_b32_e32 v143, 16, v194
	v_add_u32_e32 v144, 64, v144
	v_cmp_lt_i32_e32 vcc, v143, v144
	v_lshl_add_u32 v142, s61, 8, v146
	v_lshl_or_b32 v140, s8, 8, v148
	v_cndmask_b32_e32 v143, v194, v143, vcc
	v_lshlrev_b32_e32 v151, 2, v143
	v_xor_b32_e32 v143, 32, v194
	v_cmp_lt_i32_e32 vcc, v143, v144
	v_ashrrev_i32_e32 v141, 31, v140
	s_lshl_b32 s48, s8, 2
	v_cndmask_b32_e32 v143, v194, v143, vcc
	v_lshlrev_b32_e32 v150, 2, v143
	v_ashrrev_i32_e32 v143, 31, v142
	v_lshlrev_b64 v[144:145], 10, v[142:143]
	v_lshl_add_u64 v[144:145], v[144:145], 0, v[140:141]
	v_lshl_add_u64 v[144:145], v[144:145], 1, s[86:87]
	s_ashr_i32 s49, s48, 31
	s_waitcnt vmcnt(11)
	s_nop 1
	v_mov_b32_e32 v152, v178
	v_mov_b32_e32 v153, v179
	v_mov_b32_e32 v154, v180
	v_mov_b32_e32 v155, v181
	v_lshlrev_b32_e32 v156, 16, v152
	v_and_b32_e32 v157, 0xffff0000, v152
	v_lshlrev_b32_e32 v152, 16, v153
	v_and_b32_e32 v153, 0xffff0000, v153
	v_lshlrev_b32_e32 v158, 16, v154
	v_and_b32_e32 v159, 0xffff0000, v154
	v_lshlrev_b32_e32 v154, 16, v155
	v_and_b32_e32 v155, 0xffff0000, v155
	v_pk_fma_f32 v[128:129], v[128:129], 0.5, v[152:153] op_sel_hi:[1,0,1]
	v_pk_fma_f32 v[126:127], v[126:127], 0.5, v[156:157] op_sel_hi:[1,0,1]
	v_pk_fma_f32 v[152:153], v[124:125], 0.5, v[154:155] op_sel_hi:[1,0,1]
	v_pk_fma_f32 v[124:125], v[122:123], 0.5, v[158:159] op_sel_hi:[1,0,1]
	v_mul_f32_e32 v122, v127, v127
	v_mul_f32_e32 v123, v129, v129
	v_fmac_f32_e32 v122, v126, v126
	v_fmac_f32_e32 v123, v128, v128
	v_add_f32_e32 v122, v122, v123
	v_mul_f32_e32 v123, v125, v125
	v_mul_f32_e32 v154, v153, v153
	v_fmac_f32_e32 v123, v124, v124
	v_fmac_f32_e32 v154, v152, v152
	v_add_f32_e32 v123, v123, v154
	v_add_f32_e32 v154, v122, v123
	v_cvt_pk_bf16_f32 v122, v126, v127
	v_cvt_pk_bf16_f32 v123, v128, v129
	v_cvt_pk_bf16_f32 v124, v124, v125
	v_cvt_pk_bf16_f32 v125, v152, v153
	global_store_dwordx4 v[144:145], v[122:125], off
	s_waitcnt vmcnt(11)
	s_nop 1
	v_mov_b32_e32 v122, v182
	v_mov_b32_e32 v123, v183
	v_mov_b32_e32 v124, v184
	v_mov_b32_e32 v125, v185
	v_lshlrev_b32_e32 v126, 16, v122
	v_and_b32_e32 v127, 0xffff0000, v122
	v_lshlrev_b32_e32 v122, 16, v123
	v_and_b32_e32 v123, 0xffff0000, v123
	v_lshlrev_b32_e32 v128, 16, v124
	v_and_b32_e32 v129, 0xffff0000, v124
	v_lshlrev_b32_e32 v124, 16, v125
	v_and_b32_e32 v125, 0xffff0000, v125
	v_pk_fma_f32 v[120:121], v[120:121], 0.5, v[122:123] op_sel_hi:[1,0,1]
	v_pk_fma_f32 v[118:119], v[118:119], 0.5, v[126:127] op_sel_hi:[1,0,1]
	v_pk_fma_f32 v[122:123], v[116:117], 0.5, v[124:125] op_sel_hi:[1,0,1]
	v_pk_fma_f32 v[116:117], v[114:115], 0.5, v[128:129] op_sel_hi:[1,0,1]
	v_mul_f32_e32 v114, v119, v119
	v_mul_f32_e32 v115, v121, v121
	v_fmac_f32_e32 v114, v118, v118
	v_fmac_f32_e32 v115, v120, v120
	v_add_f32_e32 v114, v114, v115
	v_mul_f32_e32 v115, v117, v117
	v_mul_f32_e32 v124, v123, v123
	v_fmac_f32_e32 v115, v116, v116
	v_fmac_f32_e32 v124, v122, v122
	v_add_f32_e32 v115, v115, v124
	v_add_f32_e32 v114, v114, v115
	v_add_f32_e32 v124, v154, v114
	v_cvt_pk_bf16_f32 v114, v118, v119
	v_cvt_pk_bf16_f32 v115, v120, v121
	v_cvt_pk_bf16_f32 v116, v116, v117
	v_cvt_pk_bf16_f32 v117, v122, v123
	global_store_dwordx4 v[144:145], v[114:117], off offset:256
	ds_bpermute_b32 v114, v151, v124
	s_waitcnt lgkmcnt(0)
	v_add_f32_e32 v114, v124, v114
	ds_bpermute_b32 v115, v150, v114
	s_and_saveexec_b64 s[12:13], s[38:39]
	v_lshlrev_b64 v[116:117], 6, v[142:143]
	v_lshl_add_u64 v[116:117], s[88:89], 0, v[116:117]
	v_lshl_add_u64 v[116:117], s[48:49], 2, v[116:117]
	s_lshl_b32 s8, s56, 2
	v_lshl_add_u64 v[116:117], v[116:117], 0, s[8:9]
	s_waitcnt lgkmcnt(0)
	v_add_f32_e32 v114, v114, v115
	global_store_dword v[116:117], v114, off
.LBB0_1225:
	s_or_b64 exec, exec, s[12:13]
	s_mov_b64 vcc, 0x50000
	v_lshl_add_u64 v[162:163], v[160:161], 0, vcc
	global_load_dwordx4 v[178:181], v[162:163], off
	global_load_dwordx4 v[182:185], v[162:163], off offset:256
	v_or_b32_e32 v114, 16, v142
	s_waitcnt lgkmcnt(0)
	v_ashrrev_i32_e32 v115, 31, v114
	v_lshlrev_b64 v[116:117], 10, v[114:115]
	v_lshl_add_u64 v[116:117], v[116:117], 0, v[140:141]
	v_lshl_add_u64 v[116:117], v[116:117], 1, s[86:87]
	s_waitcnt vmcnt(14)
	s_nop 1
	v_mov_b32_e32 v118, v186
	v_mov_b32_e32 v119, v187
	v_mov_b32_e32 v120, v188
	v_mov_b32_e32 v121, v189
	v_lshlrev_b32_e32 v122, 16, v118
	v_and_b32_e32 v123, 0xffff0000, v118
	v_lshlrev_b32_e32 v118, 16, v119
	v_and_b32_e32 v119, 0xffff0000, v119
	v_lshlrev_b32_e32 v124, 16, v120
	v_and_b32_e32 v125, 0xffff0000, v120
	v_lshlrev_b32_e32 v120, 16, v121
	v_and_b32_e32 v121, 0xffff0000, v121
	v_pk_fma_f32 v[112:113], v[112:113], 0.5, v[118:119] op_sel_hi:[1,0,1]
	v_pk_fma_f32 v[110:111], v[110:111], 0.5, v[122:123] op_sel_hi:[1,0,1]
	v_pk_fma_f32 v[118:119], v[108:109], 0.5, v[120:121] op_sel_hi:[1,0,1]
	v_pk_fma_f32 v[108:109], v[106:107], 0.5, v[124:125] op_sel_hi:[1,0,1]
	v_mul_f32_e32 v106, v111, v111
	v_mul_f32_e32 v107, v113, v113
	v_fmac_f32_e32 v106, v110, v110
	v_fmac_f32_e32 v107, v112, v112
	v_add_f32_e32 v106, v106, v107
	v_mul_f32_e32 v107, v109, v109
	v_mul_f32_e32 v120, v119, v119
	v_fmac_f32_e32 v107, v108, v108
	v_fmac_f32_e32 v120, v118, v118
	v_add_f32_e32 v107, v107, v120
	v_add_f32_e32 v120, v106, v107
	v_cvt_pk_bf16_f32 v106, v110, v111
	v_cvt_pk_bf16_f32 v107, v112, v113
	v_cvt_pk_bf16_f32 v108, v108, v109
	v_cvt_pk_bf16_f32 v109, v118, v119
	global_store_dwordx4 v[116:117], v[106:109], off
	s_waitcnt vmcnt(14)
; DI unsigned pk2(float lo, float hi) { return pg8::cvt_pk_bf16(lo, hi); }
; DI float bflo(unsigned w) { return __uint_as_float(w << 16); }
; DI float bfhi(unsigned w) { return __uint_as_float(w & 0xffff0000u); }
;     DI void operator()(const f32x4 (&acc)[2][2][4][2], const pg8::Unit& u, int wr, int wc, int fr, int fq) const {
;     ...
;         for (int ai = 0; ai < 2; ++ai)
; #pragma unroll
;             for (int m = 0; m < 4; ++m) {
;                 const int row = row0 + ai * 128 + m * 16; float ss = 0.f;
; #pragma unroll
;                 for (int bj = 0; bj < 2; ++bj) {
;                     const size_t off = (size_t)row * DM + col0 + bj * 128;
;                     f32x4 b0, b1;
;                     if (base32) { b0 = *(const f32x4*)(base32 + off); b1 = *(const f32x4*)(base32 + off + 4); }
;                     else { const u32x4 bb = *(const u32x4*)(XB + off); b0 = (f32x4){bflo(bb.x), bfhi(bb.x), bflo(bb.y), bfhi(bb.y)}; b1 = (f32x4){bflo(bb.z), bfhi(bb.z), bflo(bb.w), bfhi(bb.w)}; }
;                     const f32x4 v0 = b0 + acc[ai][bj][m][0] * alpha, v1 = b1 + acc[ai][bj][m][1] * alpha;
;                     ss += ((v0[0] * v0[0] + v0[1] * v0[1]) + (v0[2] * v0[2] + v0[3] * v0[3])) + ((v1[0] * v1[0] + v1[1] * v1[1]) + (v1[2] * v1[2] + v1[3] * v1[3]));
;                     u32x4 w; w.x = pk2(v0[0], v0[1]); w.y = pk2(v0[2], v0[3]); w.z = pk2(v1[0], v1[1]); w.w = pk2(v1[2], v1[3]);
;                     *(u32x4*)(XB + off) = w;
;                 }
;                 ss += __shfl_xor(ss, 16); ss += __shfl_xor(ss, 32);
;                 if (fq == 0) ssq[(size_t)row * 16 + u.pn * 4 + wc] = ss;
;                 asm volatile("" ::: "memory");
;             }
	s_nop 1
	v_mov_b32_e32 v106, v202
	v_mov_b32_e32 v107, v203
	v_mov_b32_e32 v108, v204
	v_mov_b32_e32 v109, v205
	v_lshlrev_b32_e32 v110, 16, v106
	v_and_b32_e32 v111, 0xffff0000, v106
	v_lshlrev_b32_e32 v106, 16, v107
	v_and_b32_e32 v107, 0xffff0000, v107
	v_lshlrev_b32_e32 v112, 16, v108
	v_and_b32_e32 v113, 0xffff0000, v108
	v_lshlrev_b32_e32 v108, 16, v109
	v_and_b32_e32 v109, 0xffff0000, v109
	v_pk_fma_f32 v[104:105], v[104:105], 0.5, v[106:107] op_sel_hi:[1,0,1]
	v_pk_fma_f32 v[102:103], v[102:103], 0.5, v[110:111] op_sel_hi:[1,0,1]
	v_pk_fma_f32 v[106:107], v[100:101], 0.5, v[108:109] op_sel_hi:[1,0,1]
	v_pk_fma_f32 v[100:101], v[98:99], 0.5, v[112:113] op_sel_hi:[1,0,1]
	v_mul_f32_e32 v98, v103, v103
	v_mul_f32_e32 v99, v105, v105
	v_fmac_f32_e32 v98, v102, v102
	v_fmac_f32_e32 v99, v104, v104
	v_add_f32_e32 v98, v98, v99
	v_mul_f32_e32 v99, v101, v101
	v_mul_f32_e32 v108, v107, v107
	v_fmac_f32_e32 v99, v100, v100
	v_fmac_f32_e32 v108, v106, v106
	v_add_f32_e32 v99, v99, v108
	v_add_f32_e32 v98, v98, v99
	v_add_f32_e32 v108, v120, v98
	v_cvt_pk_bf16_f32 v98, v102, v103
	v_cvt_pk_bf16_f32 v99, v104, v105
	v_cvt_pk_bf16_f32 v100, v100, v101
	v_cvt_pk_bf16_f32 v101, v106, v107
	global_store_dwordx4 v[116:117], v[98:101], off offset:256
	ds_bpermute_b32 v98, v151, v108
	s_waitcnt lgkmcnt(0)
	v_add_f32_e32 v98, v108, v98
	ds_bpermute_b32 v99, v150, v98
	s_and_saveexec_b64 s[12:13], s[38:39]
	v_lshlrev_b64 v[100:101], 6, v[114:115]
	v_lshl_add_u64 v[100:101], s[88:89], 0, v[100:101]
	v_lshl_add_u64 v[100:101], s[48:49], 2, v[100:101]
	s_lshl_b32 s8, s56, 2
	v_lshl_add_u64 v[100:101], v[100:101], 0, s[8:9]
	s_waitcnt lgkmcnt(0)
	v_add_f32_e32 v98, v98, v99
	global_store_dword v[100:101], v98, off
.LBB0_1227:
	s_or_b64 exec, exec, s[12:13]
	s_mov_b64 vcc, 0x58000
	v_lshl_add_u64 v[162:163], v[160:161], 0, vcc
	global_load_dwordx4 v[186:189], v[162:163], off
	global_load_dwordx4 v[202:205], v[162:163], off offset:256
	v_or_b32_e32 v98, 32, v142
	s_waitcnt lgkmcnt(0)
	v_ashrrev_i32_e32 v99, 31, v98
	v_lshlrev_b64 v[100:101], 10, v[98:99]
	v_lshl_add_u64 v[100:101], v[100:101], 0, v[140:141]
	v_lshl_add_u64 v[100:101], v[100:101], 1, s[86:87]
	s_waitcnt vmcnt(17)
	s_nop 1
	v_mov_b32_e32 v102, v206
	v_mov_b32_e32 v103, v207
	v_mov_b32_e32 v104, v208
	v_mov_b32_e32 v105, v209
	v_lshlrev_b32_e32 v106, 16, v102
	v_and_b32_e32 v107, 0xffff0000, v102
	v_lshlrev_b32_e32 v102, 16, v103
	v_and_b32_e32 v103, 0xffff0000, v103
	v_lshlrev_b32_e32 v108, 16, v104
	v_and_b32_e32 v109, 0xffff0000, v104
	v_lshlrev_b32_e32 v104, 16, v105
	v_and_b32_e32 v105, 0xffff0000, v105
	v_pk_fma_f32 v[96:97], v[96:97], 0.5, v[102:103] op_sel_hi:[1,0,1]
	v_pk_fma_f32 v[94:95], v[94:95], 0.5, v[106:107] op_sel_hi:[1,0,1]
	v_pk_fma_f32 v[102:103], v[92:93], 0.5, v[104:105] op_sel_hi:[1,0,1]
	v_pk_fma_f32 v[92:93], v[90:91], 0.5, v[108:109] op_sel_hi:[1,0,1]
	v_mul_f32_e32 v90, v95, v95
	v_mul_f32_e32 v91, v97, v97
	v_fmac_f32_e32 v90, v94, v94
	v_fmac_f32_e32 v91, v96, v96
	v_add_f32_e32 v90, v90, v91
	v_mul_f32_e32 v91, v93, v93
	v_mul_f32_e32 v104, v103, v103
	v_fmac_f32_e32 v91, v92, v92
	v_fmac_f32_e32 v104, v102, v102
	v_add_f32_e32 v91, v91, v104
	v_add_f32_e32 v104, v90, v91
	v_cvt_pk_bf16_f32 v90, v94, v95
	v_cvt_pk_bf16_f32 v91, v96, v97
	v_cvt_pk_bf16_f32 v92, v92, v93
	v_cvt_pk_bf16_f32 v93, v102, v103
	global_store_dwordx4 v[100:101], v[90:93], off
	s_waitcnt vmcnt(17)
	s_nop 1
	v_mov_b32_e32 v90, v210
	v_mov_b32_e32 v91, v211
	v_mov_b32_e32 v92, v212
	v_mov_b32_e32 v93, v213
	v_lshlrev_b32_e32 v94, 16, v90
	v_and_b32_e32 v95, 0xffff0000, v90
	v_lshlrev_b32_e32 v90, 16, v91
	v_and_b32_e32 v91, 0xffff0000, v91
	v_lshlrev_b32_e32 v96, 16, v92
	v_and_b32_e32 v97, 0xffff0000, v92
	v_lshlrev_b32_e32 v92, 16, v93
	v_and_b32_e32 v93, 0xffff0000, v93
	v_pk_fma_f32 v[88:89], v[88:89], 0.5, v[90:91] op_sel_hi:[1,0,1]
	v_pk_fma_f32 v[86:87], v[86:87], 0.5, v[94:95] op_sel_hi:[1,0,1]
	v_pk_fma_f32 v[90:91], v[84:85], 0.5, v[92:93] op_sel_hi:[1,0,1]
	v_pk_fma_f32 v[84:85], v[82:83], 0.5, v[96:97] op_sel_hi:[1,0,1]
	v_mul_f32_e32 v82, v87, v87
	v_mul_f32_e32 v83, v89, v89
	v_fmac_f32_e32 v82, v86, v86
	v_fmac_f32_e32 v83, v88, v88
	v_add_f32_e32 v82, v82, v83
	v_mul_f32_e32 v83, v85, v85
	v_mul_f32_e32 v92, v91, v91
	v_fmac_f32_e32 v83, v84, v84
	v_fmac_f32_e32 v92, v90, v90
	v_add_f32_e32 v83, v83, v92
	v_add_f32_e32 v82, v82, v83
	v_add_f32_e32 v92, v104, v82
	v_cvt_pk_bf16_f32 v82, v86, v87
	v_cvt_pk_bf16_f32 v83, v88, v89
	v_cvt_pk_bf16_f32 v84, v84, v85
	v_cvt_pk_bf16_f32 v85, v90, v91
	global_store_dwordx4 v[100:101], v[82:85], off offset:256
	ds_bpermute_b32 v82, v151, v92
	s_waitcnt lgkmcnt(0)
	v_add_f32_e32 v82, v92, v82
	ds_bpermute_b32 v83, v150, v82
	s_and_saveexec_b64 s[12:13], s[38:39]
	v_lshlrev_b64 v[84:85], 6, v[98:99]
	v_lshl_add_u64 v[84:85], s[88:89], 0, v[84:85]
	v_lshl_add_u64 v[84:85], s[48:49], 2, v[84:85]
	s_lshl_b32 s8, s56, 2
	v_lshl_add_u64 v[84:85], v[84:85], 0, s[8:9]
	s_waitcnt lgkmcnt(0)
	v_add_f32_e32 v82, v82, v83
	global_store_dword v[84:85], v82, off
; DI unsigned pk2(float lo, float hi) { return pg8::cvt_pk_bf16(lo, hi); }
; DI float bflo(unsigned w) { return __uint_as_float(w << 16); }
; DI float bfhi(unsigned w) { return __uint_as_float(w & 0xffff0000u); }
;     DI void operator()(const f32x4 (&acc)[2][2][4][2], const pg8::Unit& u, int wr, int wc, int fr, int fq) const {
;     ...
;         for (int ai = 0; ai < 2; ++ai)
; #pragma unroll
;             for (int m = 0; m < 4; ++m) {
;                 const int row = row0 + ai * 128 + m * 16; float ss = 0.f;
; #pragma unroll
;                 for (int bj = 0; bj < 2; ++bj) {
;                     const size_t off = (size_t)row * DM + col0 + bj * 128;
;                     f32x4 b0, b1;
;                     if (base32) { b0 = *(const f32x4*)(base32 + off); b1 = *(const f32x4*)(base32 + off + 4); }
;                     else { const u32x4 bb = *(const u32x4*)(XB + off); b0 = (f32x4){bflo(bb.x), bfhi(bb.x), bflo(bb.y), bfhi(bb.y)}; b1 = (f32x4){bflo(bb.z), bfhi(bb.z), bflo(bb.w), bfhi(bb.w)}; }
;                     const f32x4 v0 = b0 + acc[ai][bj][m][0] * alpha, v1 = b1 + acc[ai][bj][m][1] * alpha;
;                     ss += ((v0[0] * v0[0] + v0[1] * v0[1]) + (v0[2] * v0[2] + v0[3] * v0[3])) + ((v1[0] * v1[0] + v1[1] * v1[1]) + (v1[2] * v1[2] + v1[3] * v1[3]));
;                     u32x4 w; w.x = pk2(v0[0], v0[1]); w.y = pk2(v0[2], v0[3]); w.z = pk2(v1[0], v1[1]); w.w = pk2(v1[2], v1[3]);
;                     *(u32x4*)(XB + off) = w;
;                 }
;                 ss += __shfl_xor(ss, 16); ss += __shfl_xor(ss, 32);
;                 if (fq == 0) ssq[(size_t)row * 16 + u.pn * 4 + wc] = ss;
;                 asm volatile("" ::: "memory");
;             }
.LBB0_1229:
	s_or_b64 exec, exec, s[12:13]
	v_or_b32_e32 v82, 48, v142
	s_waitcnt lgkmcnt(0)
	v_ashrrev_i32_e32 v83, 31, v82
	v_lshlrev_b64 v[84:85], 10, v[82:83]
	v_lshl_add_u64 v[84:85], v[84:85], 0, v[140:141]
	v_lshl_add_u64 v[84:85], v[84:85], 1, s[86:87]
	s_waitcnt vmcnt(18)
	s_nop 1
	v_mov_b32_e32 v86, v214
	v_mov_b32_e32 v87, v215
	v_mov_b32_e32 v88, v216
	v_mov_b32_e32 v89, v217
	v_lshlrev_b32_e32 v90, 16, v86
	v_and_b32_e32 v91, 0xffff0000, v86
	v_lshlrev_b32_e32 v86, 16, v87
	v_and_b32_e32 v87, 0xffff0000, v87
	v_lshlrev_b32_e32 v92, 16, v88
	v_and_b32_e32 v93, 0xffff0000, v88
	v_lshlrev_b32_e32 v88, 16, v89
	v_and_b32_e32 v89, 0xffff0000, v89
	v_pk_fma_f32 v[80:81], v[80:81], 0.5, v[86:87] op_sel_hi:[1,0,1]
	v_pk_fma_f32 v[78:79], v[78:79], 0.5, v[90:91] op_sel_hi:[1,0,1]
	v_pk_fma_f32 v[86:87], v[76:77], 0.5, v[88:89] op_sel_hi:[1,0,1]
	v_pk_fma_f32 v[76:77], v[74:75], 0.5, v[92:93] op_sel_hi:[1,0,1]
	v_mul_f32_e32 v74, v79, v79
	v_mul_f32_e32 v75, v81, v81
	v_fmac_f32_e32 v74, v78, v78
	v_fmac_f32_e32 v75, v80, v80
	v_add_f32_e32 v74, v74, v75
	v_mul_f32_e32 v75, v77, v77
	v_mul_f32_e32 v88, v87, v87
	v_fmac_f32_e32 v75, v76, v76
	v_fmac_f32_e32 v88, v86, v86
	v_add_f32_e32 v75, v75, v88
	v_add_f32_e32 v88, v74, v75
	v_cvt_pk_bf16_f32 v74, v78, v79
	v_cvt_pk_bf16_f32 v75, v80, v81
	v_cvt_pk_bf16_f32 v76, v76, v77
	v_cvt_pk_bf16_f32 v77, v86, v87
	global_store_dwordx4 v[84:85], v[74:77], off
	s_waitcnt vmcnt(18)
	s_nop 1
	v_mov_b32_e32 v74, v218
	v_mov_b32_e32 v75, v219
	v_mov_b32_e32 v76, v220
	v_mov_b32_e32 v77, v221
	v_lshlrev_b32_e32 v78, 16, v74
	v_and_b32_e32 v79, 0xffff0000, v74
	v_lshlrev_b32_e32 v74, 16, v75
	v_and_b32_e32 v75, 0xffff0000, v75
	v_lshlrev_b32_e32 v80, 16, v76
	v_and_b32_e32 v81, 0xffff0000, v76
	v_lshlrev_b32_e32 v76, 16, v77
	v_and_b32_e32 v77, 0xffff0000, v77
	v_pk_fma_f32 v[72:73], v[72:73], 0.5, v[74:75] op_sel_hi:[1,0,1]
	v_pk_fma_f32 v[70:71], v[70:71], 0.5, v[78:79] op_sel_hi:[1,0,1]
	v_pk_fma_f32 v[74:75], v[68:69], 0.5, v[76:77] op_sel_hi:[1,0,1]
	v_pk_fma_f32 v[68:69], v[66:67], 0.5, v[80:81] op_sel_hi:[1,0,1]
	v_mul_f32_e32 v66, v71, v71
	v_mul_f32_e32 v67, v73, v73
	v_fmac_f32_e32 v66, v70, v70
	v_fmac_f32_e32 v67, v72, v72
	v_add_f32_e32 v66, v66, v67
	v_mul_f32_e32 v67, v69, v69
	v_mul_f32_e32 v76, v75, v75
	v_fmac_f32_e32 v67, v68, v68
	v_fmac_f32_e32 v76, v74, v74
	v_add_f32_e32 v67, v67, v76
	v_add_f32_e32 v66, v66, v67
	v_add_f32_e32 v76, v88, v66
	v_cvt_pk_bf16_f32 v66, v70, v71
	v_cvt_pk_bf16_f32 v67, v72, v73
	v_cvt_pk_bf16_f32 v68, v68, v69
	v_cvt_pk_bf16_f32 v69, v74, v75
	global_store_dwordx4 v[84:85], v[66:69], off offset:256
	ds_bpermute_b32 v66, v151, v76
	s_waitcnt lgkmcnt(0)
	v_add_f32_e32 v66, v76, v66
	ds_bpermute_b32 v67, v150, v66
	s_and_saveexec_b64 s[12:13], s[38:39]
	v_lshlrev_b64 v[68:69], 6, v[82:83]
	v_lshl_add_u64 v[68:69], s[88:89], 0, v[68:69]
	v_lshl_add_u64 v[68:69], s[48:49], 2, v[68:69]
	s_lshl_b32 s8, s56, 2
	v_lshl_add_u64 v[68:69], v[68:69], 0, s[8:9]
	s_waitcnt lgkmcnt(0)
	v_add_f32_e32 v66, v66, v67
	global_store_dword v[68:69], v66, off
.LBB0_1231:
	s_or_b64 exec, exec, s[12:13]
	v_add_u32_e32 v66, 0x80, v142
	s_waitcnt lgkmcnt(0)
	v_ashrrev_i32_e32 v67, 31, v66
	v_lshlrev_b64 v[68:69], 10, v[66:67]
	v_lshl_add_u64 v[68:69], v[68:69], 0, v[140:141]
	v_lshl_add_u64 v[68:69], v[68:69], 1, s[86:87]
	s_waitcnt vmcnt(19)
	s_nop 1
	v_mov_b32_e32 v70, v222
	v_mov_b32_e32 v71, v223
	v_mov_b32_e32 v72, v224
	v_mov_b32_e32 v73, v225
	v_lshlrev_b32_e32 v74, 16, v70
	v_and_b32_e32 v75, 0xffff0000, v70
	v_lshlrev_b32_e32 v70, 16, v71
	v_and_b32_e32 v71, 0xffff0000, v71
	v_lshlrev_b32_e32 v76, 16, v72
	v_and_b32_e32 v77, 0xffff0000, v72
	v_lshlrev_b32_e32 v72, 16, v73
	v_and_b32_e32 v73, 0xffff0000, v73
	v_pk_fma_f32 v[64:65], v[64:65], 0.5, v[70:71] op_sel_hi:[1,0,1]
	v_pk_fma_f32 v[62:63], v[62:63], 0.5, v[74:75] op_sel_hi:[1,0,1]
	v_pk_fma_f32 v[70:71], v[60:61], 0.5, v[72:73] op_sel_hi:[1,0,1]
	v_pk_fma_f32 v[60:61], v[58:59], 0.5, v[76:77] op_sel_hi:[1,0,1]
	v_mul_f32_e32 v58, v63, v63
	v_mul_f32_e32 v59, v65, v65
	v_fmac_f32_e32 v58, v62, v62
	v_fmac_f32_e32 v59, v64, v64
	v_add_f32_e32 v58, v58, v59
	v_mul_f32_e32 v59, v61, v61
	v_mul_f32_e32 v72, v71, v71
	v_fmac_f32_e32 v59, v60, v60
	v_fmac_f32_e32 v72, v70, v70
	v_add_f32_e32 v59, v59, v72
	v_add_f32_e32 v72, v58, v59
	v_cvt_pk_bf16_f32 v58, v62, v63
	v_cvt_pk_bf16_f32 v59, v64, v65
	v_cvt_pk_bf16_f32 v60, v60, v61
	v_cvt_pk_bf16_f32 v61, v70, v71
	global_store_dwordx4 v[68:69], v[58:61], off
	s_waitcnt vmcnt(19)
	s_nop 1
	v_mov_b32_e32 v58, v226
	v_mov_b32_e32 v59, v227
	v_mov_b32_e32 v60, v228
	v_mov_b32_e32 v61, v229
	v_lshlrev_b32_e32 v62, 16, v58
	v_and_b32_e32 v63, 0xffff0000, v58
	v_lshlrev_b32_e32 v58, 16, v59
	v_and_b32_e32 v59, 0xffff0000, v59
	v_lshlrev_b32_e32 v64, 16, v60
	v_and_b32_e32 v65, 0xffff0000, v60
	v_lshlrev_b32_e32 v60, 16, v61
	v_and_b32_e32 v61, 0xffff0000, v61
	v_pk_fma_f32 v[56:57], v[56:57], 0.5, v[58:59] op_sel_hi:[1,0,1]
	v_pk_fma_f32 v[54:55], v[54:55], 0.5, v[62:63] op_sel_hi:[1,0,1]
	v_pk_fma_f32 v[58:59], v[52:53], 0.5, v[60:61] op_sel_hi:[1,0,1]
	v_pk_fma_f32 v[52:53], v[50:51], 0.5, v[64:65] op_sel_hi:[1,0,1]
	v_mul_f32_e32 v50, v55, v55
	v_mul_f32_e32 v51, v57, v57
	v_fmac_f32_e32 v50, v54, v54
	v_fmac_f32_e32 v51, v56, v56
	v_add_f32_e32 v50, v50, v51
	v_mul_f32_e32 v51, v53, v53
	v_mul_f32_e32 v60, v59, v59
	v_fmac_f32_e32 v51, v52, v52
	v_fmac_f32_e32 v60, v58, v58
	v_add_f32_e32 v51, v51, v60
	v_add_f32_e32 v50, v50, v51
	v_add_f32_e32 v60, v72, v50
	v_cvt_pk_bf16_f32 v50, v54, v55
	v_cvt_pk_bf16_f32 v51, v56, v57
	v_cvt_pk_bf16_f32 v52, v52, v53
	v_cvt_pk_bf16_f32 v53, v58, v59
	global_store_dwordx4 v[68:69], v[50:53], off offset:256
	ds_bpermute_b32 v50, v151, v60
	s_waitcnt lgkmcnt(0)
	v_add_f32_e32 v50, v60, v50
	ds_bpermute_b32 v51, v150, v50
	s_and_saveexec_b64 s[12:13], s[38:39]
	v_lshlrev_b64 v[52:53], 6, v[66:67]
	v_lshl_add_u64 v[52:53], s[88:89], 0, v[52:53]
	v_lshl_add_u64 v[52:53], s[48:49], 2, v[52:53]
	s_lshl_b32 s8, s56, 2
	v_lshl_add_u64 v[52:53], v[52:53], 0, s[8:9]
	s_waitcnt lgkmcnt(0)
	v_add_f32_e32 v50, v50, v51
	global_store_dword v[52:53], v50, off
; DI unsigned pk2(float lo, float hi) { return pg8::cvt_pk_bf16(lo, hi); }
; DI float bflo(unsigned w) { return __uint_as_float(w << 16); }
; DI float bfhi(unsigned w) { return __uint_as_float(w & 0xffff0000u); }
;     DI void operator()(const f32x4 (&acc)[2][2][4][2], const pg8::Unit& u, int wr, int wc, int fr, int fq) const {
;     ...
;         for (int ai = 0; ai < 2; ++ai)
; #pragma unroll
;             for (int m = 0; m < 4; ++m) {
;                 const int row = row0 + ai * 128 + m * 16; float ss = 0.f;
; #pragma unroll
;                 for (int bj = 0; bj < 2; ++bj) {
;                     const size_t off = (size_t)row * DM + col0 + bj * 128;
;                     f32x4 b0, b1;
;                     if (base32) { b0 = *(const f32x4*)(base32 + off); b1 = *(const f32x4*)(base32 + off + 4); }
;                     else { const u32x4 bb = *(const u32x4*)(XB + off); b0 = (f32x4){bflo(bb.x), bfhi(bb.x), bflo(bb.y), bfhi(bb.y)}; b1 = (f32x4){bflo(bb.z), bfhi(bb.z), bflo(bb.w), bfhi(bb.w)}; }
;                     const f32x4 v0 = b0 + acc[ai][bj][m][0] * alpha, v1 = b1 + acc[ai][bj][m][1] * alpha;
;                     ss += ((v0[0] * v0[0] + v0[1] * v0[1]) + (v0[2] * v0[2] + v0[3] * v0[3])) + ((v1[0] * v1[0] + v1[1] * v1[1]) + (v1[2] * v1[2] + v1[3] * v1[3]));
;                     u32x4 w; w.x = pk2(v0[0], v0[1]); w.y = pk2(v0[2], v0[3]); w.z = pk2(v1[0], v1[1]); w.w = pk2(v1[2], v1[3]);
;                     *(u32x4*)(XB + off) = w;
;                 }
;                 ss += __shfl_xor(ss, 16); ss += __shfl_xor(ss, 32);
;                 if (fq == 0) ssq[(size_t)row * 16 + u.pn * 4 + wc] = ss;
;                 asm volatile("" ::: "memory");
;             }
.LBB0_1233:
	s_or_b64 exec, exec, s[12:13]
	v_add_u32_e32 v50, 0x90, v142
	s_waitcnt lgkmcnt(0)
	v_ashrrev_i32_e32 v51, 31, v50
	v_lshlrev_b64 v[52:53], 10, v[50:51]
	v_lshl_add_u64 v[52:53], v[52:53], 0, v[140:141]
	v_lshl_add_u64 v[52:53], v[52:53], 1, s[86:87]
	s_waitcnt vmcnt(20)
	s_nop 1
	v_mov_b32_e32 v54, v230
	v_mov_b32_e32 v55, v231
	v_mov_b32_e32 v56, v232
	v_mov_b32_e32 v57, v233
	v_lshlrev_b32_e32 v58, 16, v54
	v_and_b32_e32 v59, 0xffff0000, v54
	v_lshlrev_b32_e32 v54, 16, v55
	v_and_b32_e32 v55, 0xffff0000, v55
	v_lshlrev_b32_e32 v60, 16, v56
	v_and_b32_e32 v61, 0xffff0000, v56
	v_lshlrev_b32_e32 v56, 16, v57
	v_and_b32_e32 v57, 0xffff0000, v57
	v_pk_fma_f32 v[48:49], v[48:49], 0.5, v[54:55] op_sel_hi:[1,0,1]
	v_pk_fma_f32 v[46:47], v[46:47], 0.5, v[58:59] op_sel_hi:[1,0,1]
	v_pk_fma_f32 v[54:55], v[44:45], 0.5, v[56:57] op_sel_hi:[1,0,1]
	v_pk_fma_f32 v[44:45], v[42:43], 0.5, v[60:61] op_sel_hi:[1,0,1]
	v_mul_f32_e32 v42, v47, v47
	v_mul_f32_e32 v43, v49, v49
	v_fmac_f32_e32 v42, v46, v46
	v_fmac_f32_e32 v43, v48, v48
	v_add_f32_e32 v42, v42, v43
	v_mul_f32_e32 v43, v45, v45
	v_mul_f32_e32 v56, v55, v55
	v_fmac_f32_e32 v43, v44, v44
	v_fmac_f32_e32 v56, v54, v54
	v_add_f32_e32 v43, v43, v56
	v_add_f32_e32 v56, v42, v43
	v_cvt_pk_bf16_f32 v42, v46, v47
	v_cvt_pk_bf16_f32 v43, v48, v49
	v_cvt_pk_bf16_f32 v44, v44, v45
	v_cvt_pk_bf16_f32 v45, v54, v55
	global_store_dwordx4 v[52:53], v[42:45], off
	s_waitcnt vmcnt(20)
	s_nop 1
	v_mov_b32_e32 v42, v234
	v_mov_b32_e32 v43, v235
	v_mov_b32_e32 v44, v236
	v_mov_b32_e32 v45, v237
	v_lshlrev_b32_e32 v46, 16, v42
	v_and_b32_e32 v47, 0xffff0000, v42
	v_lshlrev_b32_e32 v42, 16, v43
	v_and_b32_e32 v43, 0xffff0000, v43
	v_lshlrev_b32_e32 v48, 16, v44
	v_and_b32_e32 v49, 0xffff0000, v44
	v_lshlrev_b32_e32 v44, 16, v45
	v_and_b32_e32 v45, 0xffff0000, v45
	v_pk_fma_f32 v[40:41], v[40:41], 0.5, v[42:43] op_sel_hi:[1,0,1]
	v_pk_fma_f32 v[38:39], v[38:39], 0.5, v[46:47] op_sel_hi:[1,0,1]
	v_pk_fma_f32 v[42:43], v[36:37], 0.5, v[44:45] op_sel_hi:[1,0,1]
	v_pk_fma_f32 v[36:37], v[34:35], 0.5, v[48:49] op_sel_hi:[1,0,1]
	v_mul_f32_e32 v34, v39, v39
	v_mul_f32_e32 v35, v41, v41
	v_fmac_f32_e32 v34, v38, v38
	v_fmac_f32_e32 v35, v40, v40
	v_add_f32_e32 v34, v34, v35
	v_mul_f32_e32 v35, v37, v37
	v_mul_f32_e32 v44, v43, v43
	v_fmac_f32_e32 v35, v36, v36
	v_fmac_f32_e32 v44, v42, v42
	v_add_f32_e32 v35, v35, v44
	v_add_f32_e32 v34, v34, v35
	v_add_f32_e32 v44, v56, v34
	v_cvt_pk_bf16_f32 v34, v38, v39
	v_cvt_pk_bf16_f32 v35, v40, v41
	v_cvt_pk_bf16_f32 v36, v36, v37
	v_cvt_pk_bf16_f32 v37, v42, v43
	global_store_dwordx4 v[52:53], v[34:37], off offset:256
	ds_bpermute_b32 v34, v151, v44
	s_waitcnt lgkmcnt(0)
	v_add_f32_e32 v34, v44, v34
	ds_bpermute_b32 v35, v150, v34
	s_and_saveexec_b64 s[12:13], s[38:39]
	v_lshlrev_b64 v[36:37], 6, v[50:51]
	v_lshl_add_u64 v[36:37], s[88:89], 0, v[36:37]
	v_lshl_add_u64 v[36:37], s[48:49], 2, v[36:37]
	s_lshl_b32 s8, s56, 2
	v_lshl_add_u64 v[36:37], v[36:37], 0, s[8:9]
	s_waitcnt lgkmcnt(0)
	v_add_f32_e32 v34, v34, v35
	global_store_dword v[36:37], v34, off
; DI unsigned pk2(float lo, float hi) { return pg8::cvt_pk_bf16(lo, hi); }
; DI float bflo(unsigned w) { return __uint_as_float(w << 16); }
; DI float bfhi(unsigned w) { return __uint_as_float(w & 0xffff0000u); }
;     DI void operator()(const f32x4 (&acc)[2][2][4][2], const pg8::Unit& u, int wr, int wc, int fr, int fq) const {
;     ...
;         for (int ai = 0; ai < 2; ++ai)
; #pragma unroll
;             for (int m = 0; m < 4; ++m) {
;                 const int row = row0 + ai * 128 + m * 16; float ss = 0.f;
; #pragma unroll
;                 for (int bj = 0; bj < 2; ++bj) {
;                     const size_t off = (size_t)row * DM + col0 + bj * 128;
;                     f32x4 b0, b1;
;                     if (base32) { b0 = *(const f32x4*)(base32 + off); b1 = *(const f32x4*)(base32 + off + 4); }
;                     else { const u32x4 bb = *(const u32x4*)(XB + off); b0 = (f32x4){bflo(bb.x), bfhi(bb.x), bflo(bb.y), bfhi(bb.y)}; b1 = (f32x4){bflo(bb.z), bfhi(bb.z), bflo(bb.w), bfhi(bb.w)}; }
;                     const f32x4 v0 = b0 + acc[ai][bj][m][0] * alpha, v1 = b1 + acc[ai][bj][m][1] * alpha;
;                     ss += ((v0[0] * v0[0] + v0[1] * v0[1]) + (v0[2] * v0[2] + v0[3] * v0[3])) + ((v1[0] * v1[0] + v1[1] * v1[1]) + (v1[2] * v1[2] + v1[3] * v1[3]));
;                     u32x4 w; w.x = pk2(v0[0], v0[1]); w.y = pk2(v0[2], v0[3]); w.z = pk2(v1[0], v1[1]); w.w = pk2(v1[2], v1[3]);
;                     *(u32x4*)(XB + off) = w;
;                 }
;                 ss += __shfl_xor(ss, 16); ss += __shfl_xor(ss, 32);
;                 if (fq == 0) ssq[(size_t)row * 16 + u.pn * 4 + wc] = ss;
;                 asm volatile("" ::: "memory");
;             }
.LBB0_1235:
	s_or_b64 exec, exec, s[12:13]
	v_add_u32_e32 v34, 0xa0, v142
	s_waitcnt lgkmcnt(0)
	v_ashrrev_i32_e32 v35, 31, v34
	v_lshlrev_b64 v[36:37], 10, v[34:35]
	v_lshl_add_u64 v[36:37], v[36:37], 0, v[140:141]
	v_lshl_add_u64 v[36:37], v[36:37], 1, s[86:87]
	s_waitcnt vmcnt(18)
	s_nop 1
	v_mov_b32_e32 v38, v178
	v_mov_b32_e32 v39, v179
	v_mov_b32_e32 v40, v180
	v_mov_b32_e32 v41, v181
	v_lshlrev_b32_e32 v42, 16, v38
	v_and_b32_e32 v43, 0xffff0000, v38
	v_lshlrev_b32_e32 v38, 16, v39
	v_and_b32_e32 v39, 0xffff0000, v39
	v_lshlrev_b32_e32 v44, 16, v40
	v_and_b32_e32 v45, 0xffff0000, v40
	v_lshlrev_b32_e32 v40, 16, v41
	v_and_b32_e32 v41, 0xffff0000, v41
	v_pk_fma_f32 v[32:33], v[32:33], 0.5, v[38:39] op_sel_hi:[1,0,1]
	v_pk_fma_f32 v[30:31], v[30:31], 0.5, v[42:43] op_sel_hi:[1,0,1]
	v_pk_fma_f32 v[38:39], v[28:29], 0.5, v[40:41] op_sel_hi:[1,0,1]
	v_pk_fma_f32 v[28:29], v[26:27], 0.5, v[44:45] op_sel_hi:[1,0,1]
	v_mul_f32_e32 v26, v31, v31
	v_mul_f32_e32 v27, v33, v33
	v_fmac_f32_e32 v26, v30, v30
	v_fmac_f32_e32 v27, v32, v32
	v_add_f32_e32 v26, v26, v27
	v_mul_f32_e32 v27, v29, v29
	v_mul_f32_e32 v40, v39, v39
	v_fmac_f32_e32 v27, v28, v28
	v_fmac_f32_e32 v40, v38, v38
	v_add_f32_e32 v27, v27, v40
	v_add_f32_e32 v40, v26, v27
	v_cvt_pk_bf16_f32 v26, v30, v31
	v_cvt_pk_bf16_f32 v27, v32, v33
	v_cvt_pk_bf16_f32 v28, v28, v29
	v_cvt_pk_bf16_f32 v29, v38, v39
	global_store_dwordx4 v[36:37], v[26:29], off
	s_waitcnt vmcnt(18)
	s_nop 1
	v_mov_b32_e32 v26, v182
	v_mov_b32_e32 v27, v183
	v_mov_b32_e32 v28, v184
	v_mov_b32_e32 v29, v185
	v_lshlrev_b32_e32 v30, 16, v26
	v_and_b32_e32 v31, 0xffff0000, v26
	v_lshlrev_b32_e32 v26, 16, v27
	v_and_b32_e32 v27, 0xffff0000, v27
	v_lshlrev_b32_e32 v32, 16, v28
	v_and_b32_e32 v33, 0xffff0000, v28
	v_lshlrev_b32_e32 v28, 16, v29
	v_and_b32_e32 v29, 0xffff0000, v29
	v_pk_fma_f32 v[24:25], v[24:25], 0.5, v[26:27] op_sel_hi:[1,0,1]
	v_pk_fma_f32 v[22:23], v[22:23], 0.5, v[30:31] op_sel_hi:[1,0,1]
	v_pk_fma_f32 v[26:27], v[20:21], 0.5, v[28:29] op_sel_hi:[1,0,1]
	v_pk_fma_f32 v[20:21], v[18:19], 0.5, v[32:33] op_sel_hi:[1,0,1]
	v_mul_f32_e32 v18, v23, v23
	v_mul_f32_e32 v19, v25, v25
	v_fmac_f32_e32 v18, v22, v22
	v_fmac_f32_e32 v19, v24, v24
	v_add_f32_e32 v18, v18, v19
	v_mul_f32_e32 v19, v21, v21
	v_mul_f32_e32 v28, v27, v27
	v_fmac_f32_e32 v19, v20, v20
	v_fmac_f32_e32 v28, v26, v26
	v_add_f32_e32 v19, v19, v28
	v_add_f32_e32 v18, v18, v19
	v_add_f32_e32 v28, v40, v18
	v_cvt_pk_bf16_f32 v18, v22, v23
	v_cvt_pk_bf16_f32 v19, v24, v25
	v_cvt_pk_bf16_f32 v20, v20, v21
	v_cvt_pk_bf16_f32 v21, v26, v27
	global_store_dwordx4 v[36:37], v[18:21], off offset:256
	ds_bpermute_b32 v18, v151, v28
	s_waitcnt lgkmcnt(0)
	v_add_f32_e32 v18, v28, v18
	ds_bpermute_b32 v19, v150, v18
	s_and_saveexec_b64 s[12:13], s[38:39]
	v_lshlrev_b64 v[20:21], 6, v[34:35]
	v_lshl_add_u64 v[20:21], s[88:89], 0, v[20:21]
	v_lshl_add_u64 v[20:21], s[48:49], 2, v[20:21]
	s_lshl_b32 s8, s56, 2
	v_lshl_add_u64 v[20:21], v[20:21], 0, s[8:9]
	s_waitcnt lgkmcnt(0)
	v_add_f32_e32 v18, v18, v19
	global_store_dword v[20:21], v18, off
.LBB0_1237:
	s_or_b64 exec, exec, s[12:13]
	v_add_u32_e32 v18, 0xb0, v142
	s_waitcnt lgkmcnt(0)
	v_ashrrev_i32_e32 v19, 31, v18
	v_lshlrev_b64 v[20:21], 10, v[18:19]
	v_lshl_add_u64 v[20:21], v[20:21], 0, v[140:141]
	v_lshl_add_u64 v[20:21], v[20:21], 1, s[86:87]
	s_waitcnt vmcnt(16)
	s_nop 1
	v_mov_b32_e32 v22, v186
	v_mov_b32_e32 v23, v187
	v_mov_b32_e32 v24, v188
	v_mov_b32_e32 v25, v189
	v_lshlrev_b32_e32 v26, 16, v22
	v_and_b32_e32 v27, 0xffff0000, v22
	v_lshlrev_b32_e32 v22, 16, v23
	v_and_b32_e32 v23, 0xffff0000, v23
	v_lshlrev_b32_e32 v28, 16, v24
	v_and_b32_e32 v29, 0xffff0000, v24
	v_lshlrev_b32_e32 v24, 16, v25
	v_and_b32_e32 v25, 0xffff0000, v25
	v_pk_fma_f32 v[16:17], v[16:17], 0.5, v[22:23] op_sel_hi:[1,0,1]
	v_pk_fma_f32 v[14:15], v[14:15], 0.5, v[26:27] op_sel_hi:[1,0,1]
	v_pk_fma_f32 v[22:23], v[12:13], 0.5, v[24:25] op_sel_hi:[1,0,1]
	v_pk_fma_f32 v[12:13], v[10:11], 0.5, v[28:29] op_sel_hi:[1,0,1]
	v_mul_f32_e32 v10, v15, v15
	v_mul_f32_e32 v11, v17, v17
	v_fmac_f32_e32 v10, v14, v14
	v_fmac_f32_e32 v11, v16, v16
	v_add_f32_e32 v10, v10, v11
	v_mul_f32_e32 v11, v13, v13
	v_mul_f32_e32 v24, v23, v23
	v_fmac_f32_e32 v11, v12, v12
	v_fmac_f32_e32 v24, v22, v22
	v_add_f32_e32 v11, v11, v24
	v_add_f32_e32 v24, v10, v11
	v_cvt_pk_bf16_f32 v10, v14, v15
	v_cvt_pk_bf16_f32 v11, v16, v17
	v_cvt_pk_bf16_f32 v12, v12, v13
	v_cvt_pk_bf16_f32 v13, v22, v23
	global_store_dwordx4 v[20:21], v[10:13], off
	s_waitcnt vmcnt(16)
	s_nop 1
	v_mov_b32_e32 v10, v202
	v_mov_b32_e32 v11, v203
	v_mov_b32_e32 v12, v204
	v_mov_b32_e32 v13, v205
	v_lshlrev_b32_e32 v14, 16, v10
	v_and_b32_e32 v15, 0xffff0000, v10
	v_lshlrev_b32_e32 v10, 16, v11
	v_and_b32_e32 v11, 0xffff0000, v11
	v_lshlrev_b32_e32 v16, 16, v12
	v_and_b32_e32 v17, 0xffff0000, v12
	v_lshlrev_b32_e32 v12, 16, v13
	v_and_b32_e32 v13, 0xffff0000, v13
	v_pk_fma_f32 v[8:9], v[8:9], 0.5, v[10:11] op_sel_hi:[1,0,1]
	v_pk_fma_f32 v[6:7], v[6:7], 0.5, v[14:15] op_sel_hi:[1,0,1]
	v_pk_fma_f32 v[10:11], v[4:5], 0.5, v[12:13] op_sel_hi:[1,0,1]
	v_pk_fma_f32 v[4:5], v[2:3], 0.5, v[16:17] op_sel_hi:[1,0,1]
	v_mul_f32_e32 v2, v7, v7
	v_mul_f32_e32 v3, v9, v9
	v_fmac_f32_e32 v2, v6, v6
	v_fmac_f32_e32 v3, v8, v8
	v_add_f32_e32 v2, v2, v3
	v_mul_f32_e32 v3, v5, v5
	v_mul_f32_e32 v12, v11, v11
	v_fmac_f32_e32 v3, v4, v4
	v_fmac_f32_e32 v12, v10, v10
	v_add_f32_e32 v3, v3, v12
	v_add_f32_e32 v2, v2, v3
	v_add_f32_e32 v12, v24, v2
	v_cvt_pk_bf16_f32 v2, v6, v7
	v_cvt_pk_bf16_f32 v3, v8, v9
	v_cvt_pk_bf16_f32 v4, v4, v5
	v_cvt_pk_bf16_f32 v5, v10, v11
	global_store_dwordx4 v[20:21], v[2:5], off offset:256
	ds_bpermute_b32 v2, v151, v12
	s_waitcnt lgkmcnt(0)
	v_add_f32_e32 v2, v12, v2
	ds_bpermute_b32 v3, v150, v2
	s_and_saveexec_b64 s[12:13], s[38:39]
	v_lshlrev_b64 v[4:5], 6, v[18:19]
	v_lshl_add_u64 v[4:5], s[88:89], 0, v[4:5]
	v_lshl_add_u64 v[4:5], s[48:49], 2, v[4:5]
	s_lshl_b32 s8, s56, 2
	v_lshl_add_u64 v[4:5], v[4:5], 0, s[8:9]
	s_waitcnt lgkmcnt(0)
	v_add_f32_e32 v2, v2, v3
	global_store_dword v[4:5], v2, off
